# v51 plus MFMA bursts cleaned (priority drop before the barrier, redundant lgkmcnt wait removed)
# speedup vs baseline: 1.0079x; 1.0062x over previous
; #define PG8_STAGE(bufoff, gbase, voff) do { _Pragma("unroll") for (int _i = 0; _i < 2; ++_i) \
;         __builtin_amdgcn_global_load_lds((const unsigned*)((const char*)(gbase) + (voff)[_i]), (PG8_LAS unsigned*)(lds + (bufoff) + ldsw + _i * 8192), 16, 0, 0); } while (0)
; #define PG8_LDA(dst, b, h) do { _Pragma("unroll") for (int m = 0; m < 4; ++m) _Pragma("unroll") for (int k = 0; k < 2; ++k) dst[m][k] = *(const PG8_LAS bf16x8*)(lds + PG8_SA(b, h) + aoff + m * 2048 + k * 1024); } while (0)
; #define PG8_LDB(dst, b, h) do { _Pragma("unroll") for (int n = 0; n < 2; ++n) _Pragma("unroll") for (int k = 0; k < 2; ++k) dst[n][k] = *(const PG8_LAS bf16x8*)(lds + PG8_SB(b, h) + boff + n * 2048 + k * 1024); } while (0)
; #define PG8_MMA(ai, bj, At, Bt) do { __builtin_amdgcn_s_setprio(1); _Pragma("unroll") for (int m = 0; m < 4; ++m) _Pragma("unroll") for (int n = 0; n < 2; ++n) _Pragma("unroll") for (int k = 0; k < 2; ++k) \
;         acc[ai][bj][m][n] = __builtin_amdgcn_mfma_f32_16x16x32_bf16(Bt[n][k], At[m][k], acc[ai][bj][m][n], 0, 0, 0); __builtin_amdgcn_s_setprio(0); } while (0)
; #define PG8_WAIT_V(n) asm volatile("s_waitcnt vmcnt(" #n ")" ::: "memory")
; #define PG8_WAIT_L(n) asm volatile("s_waitcnt lgkmcnt(" #n ")" ::: "memory")
; #define PG8_BAR __builtin_amdgcn_s_barrier()
; template <class Epi, class Sched, bool ALIGN_EPI = false, bool SP2 = false>
; __device__ __forceinline__ void gemm_phase(PG8_LAS unsigned char* lds, const Gemm g, const Sched& S, const Epi& E) {
;     ...
;             const char* a1 = cA + (size_t)(t + 1) * kstep;
;             const char* a2 = last ? nA : cA + (size_t)(t + 2) * kstep; const char* b2 = last ? nB : cB + (size_t)(t + 2) * kstep;
;             const char* a3 = a2 + kstep; const char* b3 = b2 + kstep;
;             if (last && has_next) S.a_ready(nxt);
;             if constexpr (SP2) {
;             PG8_LDB(B0, 0, 0); PG8_LDB(B1, 0, 1); PG8_SCHED; PG8_LDA(At, 0, 0); PG8_STAGE(PG8_SA(1, 1), a1 + hstep, voffA);
;             PG8_WAIT_V(8); PG8_WAIT_L(0); PG8_BAR; PG8_MMA(0, 0, At, B0); PG8_MMA(0, 1, At, B1); PG8_BAR; PG8_SCHED;
;             PG8_LDA(At, 0, 1); PG8_STAGE(PG8_SB(0, 0), b2, voffB); PG8_STAGE(PG8_SB(0, 1), b2 + hstep, voffB); PG8_STAGE(PG8_SA(0, 0), a2, voffA);
;             PG8_WAIT_V(8); PG8_WAIT_L(0); PG8_BAR; PG8_MMA(1, 0, At, B0); PG8_MMA(1, 1, At, B1); PG8_BAR; PG8_SCHED;
.LBB0_301:
	s_add_u32 s38, s36, 0xfff80080
	s_addc_u32 s39, s37, -1
	s_add_i32 s61, 0, 0x10000
	s_cmp_eq_u32 s60, 28
	s_cselect_b32 s41, s11, s39
	s_cselect_b32 s40, s13, s38
	s_cselect_b32 s39, s56, s59
	s_cselect_b32 s38, s57, s58
	s_add_i32 s64, 0, 0x14000
	ds_read_b128 v[174:177], v249 offset:16384
	ds_read_b128 v[178:181], v249 offset:17408
	ds_read_b128 v[204:207], v249 offset:18432
	ds_read_b128 v[208:211], v249 offset:19456
	s_add_i32 m0, s47, 0xc000
	ds_read_b128 v[212:215], v153
	ds_read_b128 v[216:219], v153 offset:1024
	ds_read_b128 v[220:223], v153 offset:2048
	ds_read_b128 v[224:227], v153 offset:3072
	ds_read_b128 v[228:231], v153 offset:4096
	ds_read_b128 v[232:235], v153 offset:5120
	ds_read_b128 v[236:239], v153 offset:6144
	ds_read_b128 v[240:243], v153 offset:7168
	global_load_lds_dwordx4 v138, s[36:37]
	s_add_i32 m0, s47, 0xe000
	s_nop 0
	global_load_lds_dwordx4 v140, s[36:37]
	s_waitcnt vmcnt(8) lgkmcnt(0)
	s_setprio 0
	s_barrier
	v_mfma_f32_16x16x32_bf16 v[128:131], v[142:145], v[212:215], v[128:131]
	v_mfma_f32_16x16x32_bf16 v[120:123], v[154:157], v[212:215], v[120:123]
	v_mfma_f32_16x16x32_bf16 v[112:115], v[142:145], v[220:223], v[112:115]
	v_mfma_f32_16x16x32_bf16 v[104:107], v[154:157], v[220:223], v[104:107]
	v_mfma_f32_16x16x32_bf16 v[96:99], v[142:145], v[228:231], v[96:99]
	v_mfma_f32_16x16x32_bf16 v[88:91], v[154:157], v[228:231], v[88:91]
	v_mfma_f32_16x16x32_bf16 v[80:83], v[142:145], v[236:239], v[80:83]
	v_mfma_f32_16x16x32_bf16 v[72:75], v[154:157], v[236:239], v[72:75]
	v_mfma_f32_16x16x32_bf16 v[128:131], v[146:149], v[216:219], v[128:131]
	v_mfma_f32_16x16x32_bf16 v[120:123], v[158:161], v[216:219], v[120:123]
	v_mfma_f32_16x16x32_bf16 v[112:115], v[146:149], v[224:227], v[112:115]
	v_mfma_f32_16x16x32_bf16 v[104:107], v[158:161], v[224:227], v[104:107]
	v_mfma_f32_16x16x32_bf16 v[96:99], v[146:149], v[232:235], v[96:99]
	v_mfma_f32_16x16x32_bf16 v[88:91], v[158:161], v[232:235], v[88:91]
	v_mfma_f32_16x16x32_bf16 v[80:83], v[146:149], v[240:243], v[80:83]
	v_mfma_f32_16x16x32_bf16 v[72:75], v[158:161], v[240:243], v[72:75]
	v_mfma_f32_16x16x32_bf16 v[124:127], v[174:177], v[212:215], v[124:127]
	v_mfma_f32_16x16x32_bf16 v[116:119], v[204:207], v[212:215], v[116:119]
	v_mfma_f32_16x16x32_bf16 v[108:111], v[174:177], v[220:223], v[108:111]
	v_mfma_f32_16x16x32_bf16 v[100:103], v[204:207], v[220:223], v[100:103]
	v_mfma_f32_16x16x32_bf16 v[92:95], v[174:177], v[228:231], v[92:95]
	v_mfma_f32_16x16x32_bf16 v[84:87], v[204:207], v[228:231], v[84:87]
	v_mfma_f32_16x16x32_bf16 v[76:79], v[174:177], v[236:239], v[76:79]
	v_mfma_f32_16x16x32_bf16 v[68:71], v[204:207], v[236:239], v[68:71]
	v_mfma_f32_16x16x32_bf16 v[124:127], v[178:181], v[216:219], v[124:127]
	v_mfma_f32_16x16x32_bf16 v[116:119], v[208:211], v[216:219], v[116:119]
	v_mfma_f32_16x16x32_bf16 v[108:111], v[178:181], v[224:227], v[108:111]
	v_mfma_f32_16x16x32_bf16 v[100:103], v[208:211], v[224:227], v[100:103]
	v_mfma_f32_16x16x32_bf16 v[92:95], v[178:181], v[232:235], v[92:95]
	v_mfma_f32_16x16x32_bf16 v[84:87], v[208:211], v[232:235], v[84:87]
	v_mfma_f32_16x16x32_bf16 v[76:79], v[178:181], v[240:243], v[76:79]
	v_mfma_f32_16x16x32_bf16 v[68:71], v[208:211], v[240:243], v[68:71]
	s_setprio 3
	s_barrier
	s_add_i32 s61, s61, s42
	s_mov_b32 m0, s61
	ds_read_b128 v[212:215], v153 offset:16384
	ds_read_b128 v[216:219], v153 offset:17408
	ds_read_b128 v[220:223], v153 offset:18432
	ds_read_b128 v[224:227], v153 offset:19456
	ds_read_b128 v[228:231], v153 offset:20480
	ds_read_b128 v[232:235], v153 offset:21504
	ds_read_b128 v[236:239], v153 offset:22528
	ds_read_b128 v[240:243], v153 offset:23552
	global_load_lds_dwordx4 v2, s[38:39]
	s_add_i32 m0, s61, 0x2000
	s_add_u32 s62, s38, 0x80000
	s_addc_u32 s63, s39, 0
	s_add_i32 s61, s64, s42
	global_load_lds_dwordx4 v132, s[38:39]
	s_mov_b32 m0, s61
	s_nop 0
	global_load_lds_dwordx4 v2, s[62:63]
	s_add_i32 m0, s61, 0x2000
	s_nop 0
	global_load_lds_dwordx4 v132, s[62:63]
	s_mov_b32 m0, s47
	s_nop 0
	global_load_lds_dwordx4 v136, s[40:41]
	s_mov_b32 m0, s48
	s_nop 0
	global_load_lds_dwordx4 v134, s[40:41]
	s_waitcnt vmcnt(8) lgkmcnt(0)
	s_setprio 0
	s_barrier
	v_mfma_f32_16x16x32_bf16 v[64:67], v[142:145], v[212:215], v[64:67]
	v_mfma_f32_16x16x32_bf16 v[56:59], v[154:157], v[212:215], v[56:59]
	v_mfma_f32_16x16x32_bf16 v[48:51], v[142:145], v[220:223], v[48:51]
	v_mfma_f32_16x16x32_bf16 v[40:43], v[154:157], v[220:223], v[40:43]
	v_mfma_f32_16x16x32_bf16 v[32:35], v[142:145], v[228:231], v[32:35]
	v_mfma_f32_16x16x32_bf16 v[24:27], v[154:157], v[228:231], v[24:27]
	v_mfma_f32_16x16x32_bf16 v[16:19], v[142:145], v[236:239], v[16:19]
	v_mfma_f32_16x16x32_bf16 v[8:11], v[154:157], v[236:239], v[8:11]
	v_mfma_f32_16x16x32_bf16 v[64:67], v[146:149], v[216:219], v[64:67]
	v_mfma_f32_16x16x32_bf16 v[56:59], v[158:161], v[216:219], v[56:59]
	v_mfma_f32_16x16x32_bf16 v[48:51], v[146:149], v[224:227], v[48:51]
	v_mfma_f32_16x16x32_bf16 v[40:43], v[158:161], v[224:227], v[40:43]
	v_mfma_f32_16x16x32_bf16 v[32:35], v[146:149], v[232:235], v[32:35]
	v_mfma_f32_16x16x32_bf16 v[24:27], v[158:161], v[232:235], v[24:27]
	v_mfma_f32_16x16x32_bf16 v[16:19], v[146:149], v[240:243], v[16:19]
	v_mfma_f32_16x16x32_bf16 v[8:11], v[158:161], v[240:243], v[8:11]
	v_mfma_f32_16x16x32_bf16 v[60:63], v[174:177], v[212:215], v[60:63]
	ds_read_b128 v[142:145], v249 offset:32768
	v_mfma_f32_16x16x32_bf16 v[52:55], v[204:207], v[212:215], v[52:55]
	ds_read_b128 v[146:149], v249 offset:33792
	v_mfma_f32_16x16x32_bf16 v[44:47], v[174:177], v[220:223], v[44:47]
	ds_read_b128 v[154:157], v249 offset:34816
	v_mfma_f32_16x16x32_bf16 v[36:39], v[204:207], v[220:223], v[36:39]
	ds_read_b128 v[158:161], v249 offset:35840
	v_mfma_f32_16x16x32_bf16 v[28:31], v[174:177], v[228:231], v[28:31]
	v_mfma_f32_16x16x32_bf16 v[20:23], v[204:207], v[228:231], v[20:23]
	v_mfma_f32_16x16x32_bf16 v[12:15], v[174:177], v[236:239], v[12:15]
	v_mfma_f32_16x16x32_bf16 v[4:7], v[204:207], v[236:239], v[4:7]
	v_mfma_f32_16x16x32_bf16 v[60:63], v[178:181], v[216:219], v[60:63]
	v_mfma_f32_16x16x32_bf16 v[52:55], v[208:211], v[216:219], v[52:55]
	v_mfma_f32_16x16x32_bf16 v[44:47], v[178:181], v[224:227], v[44:47]
	v_mfma_f32_16x16x32_bf16 v[36:39], v[208:211], v[224:227], v[36:39]
	v_mfma_f32_16x16x32_bf16 v[28:31], v[178:181], v[232:235], v[28:31]
	v_mfma_f32_16x16x32_bf16 v[20:23], v[208:211], v[232:235], v[20:23]
	v_mfma_f32_16x16x32_bf16 v[12:15], v[178:181], v[240:243], v[12:15]
	v_mfma_f32_16x16x32_bf16 v[4:7], v[208:211], v[240:243], v[4:7]
	s_setprio 3
	s_barrier
; #define PG8_STAGE(bufoff, gbase, voff) do { _Pragma("unroll") for (int _i = 0; _i < 2; ++_i) \
;         __builtin_amdgcn_global_load_lds((const unsigned*)((const char*)(gbase) + (voff)[_i]), (PG8_LAS unsigned*)(lds + (bufoff) + ldsw + _i * 8192), 16, 0, 0); } while (0)
; #define PG8_LDA(dst, b, h) do { _Pragma("unroll") for (int m = 0; m < 4; ++m) _Pragma("unroll") for (int k = 0; k < 2; ++k) dst[m][k] = *(const PG8_LAS bf16x8*)(lds + PG8_SA(b, h) + aoff + m * 2048 + k * 1024); } while (0)
; #define PG8_LDB(dst, b, h) do { _Pragma("unroll") for (int n = 0; n < 2; ++n) _Pragma("unroll") for (int k = 0; k < 2; ++k) dst[n][k] = *(const PG8_LAS bf16x8*)(lds + PG8_SB(b, h) + boff + n * 2048 + k * 1024); } while (0)
; #define PG8_MMA(ai, bj, At, Bt) do { __builtin_amdgcn_s_setprio(1); _Pragma("unroll") for (int m = 0; m < 4; ++m) _Pragma("unroll") for (int n = 0; n < 2; ++n) _Pragma("unroll") for (int k = 0; k < 2; ++k) \
;         acc[ai][bj][m][n] = __builtin_amdgcn_mfma_f32_16x16x32_bf16(Bt[n][k], At[m][k], acc[ai][bj][m][n], 0, 0, 0); __builtin_amdgcn_s_setprio(0); } while (0)
; #define PG8_WAIT_V(n) asm volatile("s_waitcnt vmcnt(" #n ")" ::: "memory")
; #define PG8_WAIT_L(n) asm volatile("s_waitcnt lgkmcnt(" #n ")" ::: "memory")
; #define PG8_BAR __builtin_amdgcn_s_barrier()
; #define PG8_SCHED __builtin_amdgcn_sched_barrier(0)
; template <class Epi, class Sched, bool ALIGN_EPI = false, bool SP2 = false>
; __device__ __forceinline__ void gemm_phase(PG8_LAS unsigned char* lds, const Gemm g, const Sched& S, const Epi& E) {
;     ...
;             PG8_LDB(B0, 1, 0); PG8_LDB(B1, 1, 1); PG8_SCHED; PG8_LDA(At, 1, 0); PG8_STAGE(PG8_SA(0, 1), a2 + hstep, voffA);
;             PG8_WAIT_V(8); PG8_WAIT_L(0); PG8_BAR; PG8_MMA(0, 0, At, B0); PG8_MMA(0, 1, At, B1); PG8_BAR; PG8_SCHED;
;             PG8_LDA(At, 1, 1); PG8_STAGE(PG8_SB(1, 0), b3, voffB); PG8_STAGE(PG8_SB(1, 1), b3 + hstep, voffB); PG8_STAGE(PG8_SA(1, 0), a3, voffA);
;             PG8_WAIT_V(8); PG8_WAIT_L(0); PG8_BAR; PG8_MMA(1, 0, At, B0); PG8_MMA(1, 1, At, B1); PG8_BAR; PG8_SCHED;
	s_add_i32 s61, 0, 0x18000
	s_add_i32 s62, 0, 0x1c000
	ds_read_b128 v[174:177], v249 offset:49152
	ds_read_b128 v[178:181], v249 offset:50176
	ds_read_b128 v[204:207], v249 offset:51200
	ds_read_b128 v[208:211], v249 offset:52224
	s_add_u32 s100, s40, 0x80
	s_addc_u32 s101, s41, 0
	s_add_u32 s40, s40, 0x80000
	s_addc_u32 s41, s41, 0
	s_mov_b32 m0, s49
	ds_read_b128 v[212:215], v153 offset:32768
	ds_read_b128 v[216:219], v153 offset:33792
	ds_read_b128 v[220:223], v153 offset:34816
	ds_read_b128 v[224:227], v153 offset:35840
	ds_read_b128 v[228:231], v153 offset:36864
	ds_read_b128 v[232:235], v153 offset:37888
	ds_read_b128 v[236:239], v153 offset:38912
	ds_read_b128 v[240:243], v153 offset:39936
	global_load_lds_dwordx4 v136, s[40:41]
	s_mov_b32 m0, s50
	s_nop 0
	global_load_lds_dwordx4 v134, s[40:41]
	s_waitcnt vmcnt(8) lgkmcnt(0)
	s_setprio 0
	s_barrier
	v_mfma_f32_16x16x32_bf16 v[128:131], v[142:145], v[212:215], v[128:131]
	v_mfma_f32_16x16x32_bf16 v[120:123], v[154:157], v[212:215], v[120:123]
	v_mfma_f32_16x16x32_bf16 v[112:115], v[142:145], v[220:223], v[112:115]
	v_mfma_f32_16x16x32_bf16 v[104:107], v[154:157], v[220:223], v[104:107]
	v_mfma_f32_16x16x32_bf16 v[96:99], v[142:145], v[228:231], v[96:99]
	v_mfma_f32_16x16x32_bf16 v[88:91], v[154:157], v[228:231], v[88:91]
	v_mfma_f32_16x16x32_bf16 v[80:83], v[142:145], v[236:239], v[80:83]
	v_mfma_f32_16x16x32_bf16 v[72:75], v[154:157], v[236:239], v[72:75]
	v_mfma_f32_16x16x32_bf16 v[128:131], v[146:149], v[216:219], v[128:131]
	v_mfma_f32_16x16x32_bf16 v[120:123], v[158:161], v[216:219], v[120:123]
	v_mfma_f32_16x16x32_bf16 v[112:115], v[146:149], v[224:227], v[112:115]
	v_mfma_f32_16x16x32_bf16 v[104:107], v[158:161], v[224:227], v[104:107]
	v_mfma_f32_16x16x32_bf16 v[96:99], v[146:149], v[232:235], v[96:99]
	v_mfma_f32_16x16x32_bf16 v[88:91], v[158:161], v[232:235], v[88:91]
	v_mfma_f32_16x16x32_bf16 v[80:83], v[146:149], v[240:243], v[80:83]
	v_mfma_f32_16x16x32_bf16 v[72:75], v[158:161], v[240:243], v[72:75]
	v_mfma_f32_16x16x32_bf16 v[124:127], v[174:177], v[212:215], v[124:127]
	v_mfma_f32_16x16x32_bf16 v[116:119], v[204:207], v[212:215], v[116:119]
	v_mfma_f32_16x16x32_bf16 v[108:111], v[174:177], v[220:223], v[108:111]
	v_mfma_f32_16x16x32_bf16 v[100:103], v[204:207], v[220:223], v[100:103]
	v_mfma_f32_16x16x32_bf16 v[92:95], v[174:177], v[228:231], v[92:95]
	v_mfma_f32_16x16x32_bf16 v[84:87], v[204:207], v[228:231], v[84:87]
	v_mfma_f32_16x16x32_bf16 v[76:79], v[174:177], v[236:239], v[76:79]
	v_mfma_f32_16x16x32_bf16 v[68:71], v[204:207], v[236:239], v[68:71]
	v_mfma_f32_16x16x32_bf16 v[124:127], v[178:181], v[216:219], v[124:127]
	v_mfma_f32_16x16x32_bf16 v[116:119], v[208:211], v[216:219], v[116:119]
	v_mfma_f32_16x16x32_bf16 v[108:111], v[178:181], v[224:227], v[108:111]
	v_mfma_f32_16x16x32_bf16 v[100:103], v[208:211], v[224:227], v[100:103]
	v_mfma_f32_16x16x32_bf16 v[92:95], v[178:181], v[232:235], v[92:95]
	v_mfma_f32_16x16x32_bf16 v[84:87], v[208:211], v[232:235], v[84:87]
	v_mfma_f32_16x16x32_bf16 v[76:79], v[178:181], v[240:243], v[76:79]
	v_mfma_f32_16x16x32_bf16 v[68:71], v[208:211], v[240:243], v[68:71]
	s_setprio 3
	s_barrier
	s_add_i32 s40, s61, s42
	s_add_i32 m0, s40, 0xffffff80
	ds_read_b128 v[212:215], v153 offset:49152
	ds_read_b128 v[216:219], v153 offset:50176
	ds_read_b128 v[220:223], v153 offset:51200
	ds_read_b128 v[224:227], v153 offset:52224
	ds_read_b128 v[228:231], v153 offset:53248
	ds_read_b128 v[232:235], v153 offset:54272
	ds_read_b128 v[236:239], v153 offset:55296
	ds_read_b128 v[240:243], v153 offset:56320
	global_load_lds_dwordx4 v2, s[38:39] offset:128
	s_add_i32 m0, s40, 0x1f80
	s_add_i32 s40, s62, s42
	global_load_lds_dwordx4 v132, s[38:39] offset:128
	s_add_u32 s38, s38, 0x80080
	s_addc_u32 s39, s39, 0
	s_mov_b32 m0, s40
	s_nop 0
	global_load_lds_dwordx4 v2, s[38:39]
	s_add_i32 m0, s40, 0x2000
	s_nop 0
	global_load_lds_dwordx4 v132, s[38:39]
	s_mov_b32 m0, s51
	s_nop 0
	global_load_lds_dwordx4 v136, s[100:101]
	s_mov_b32 m0, s53
	s_nop 0
	global_load_lds_dwordx4 v134, s[100:101]
	s_nop 0
	s_waitcnt vmcnt(8) lgkmcnt(0)
	s_setprio 0
	s_barrier
	v_mfma_f32_16x16x32_bf16 v[64:67], v[142:145], v[212:215], v[64:67]
	v_mfma_f32_16x16x32_bf16 v[56:59], v[154:157], v[212:215], v[56:59]
	v_mfma_f32_16x16x32_bf16 v[48:51], v[142:145], v[220:223], v[48:51]
	v_mfma_f32_16x16x32_bf16 v[40:43], v[154:157], v[220:223], v[40:43]
	v_mfma_f32_16x16x32_bf16 v[32:35], v[142:145], v[228:231], v[32:35]
	v_mfma_f32_16x16x32_bf16 v[24:27], v[154:157], v[228:231], v[24:27]
	v_mfma_f32_16x16x32_bf16 v[16:19], v[142:145], v[236:239], v[16:19]
	v_mfma_f32_16x16x32_bf16 v[8:11], v[154:157], v[236:239], v[8:11]
	v_mfma_f32_16x16x32_bf16 v[64:67], v[146:149], v[216:219], v[64:67]
	v_mfma_f32_16x16x32_bf16 v[56:59], v[158:161], v[216:219], v[56:59]
	v_mfma_f32_16x16x32_bf16 v[48:51], v[146:149], v[224:227], v[48:51]
	v_mfma_f32_16x16x32_bf16 v[40:43], v[158:161], v[224:227], v[40:43]
	v_mfma_f32_16x16x32_bf16 v[32:35], v[146:149], v[232:235], v[32:35]
	v_mfma_f32_16x16x32_bf16 v[24:27], v[158:161], v[232:235], v[24:27]
	v_mfma_f32_16x16x32_bf16 v[16:19], v[146:149], v[240:243], v[16:19]
	v_mfma_f32_16x16x32_bf16 v[8:11], v[158:161], v[240:243], v[8:11]
	v_mfma_f32_16x16x32_bf16 v[60:63], v[174:177], v[212:215], v[60:63]
	ds_read_b128 v[142:145], v249
	v_mfma_f32_16x16x32_bf16 v[52:55], v[204:207], v[212:215], v[52:55]
	ds_read_b128 v[146:149], v249 offset:1024
	v_mfma_f32_16x16x32_bf16 v[44:47], v[174:177], v[220:223], v[44:47]
	ds_read_b128 v[154:157], v249 offset:2048
	v_mfma_f32_16x16x32_bf16 v[36:39], v[204:207], v[220:223], v[36:39]
	ds_read_b128 v[158:161], v249 offset:3072
	v_mfma_f32_16x16x32_bf16 v[28:31], v[174:177], v[228:231], v[28:31]
	v_mfma_f32_16x16x32_bf16 v[20:23], v[204:207], v[228:231], v[20:23]
	v_mfma_f32_16x16x32_bf16 v[12:15], v[174:177], v[236:239], v[12:15]
	v_mfma_f32_16x16x32_bf16 v[4:7], v[204:207], v[236:239], v[4:7]
	v_mfma_f32_16x16x32_bf16 v[60:63], v[178:181], v[216:219], v[60:63]
	v_mfma_f32_16x16x32_bf16 v[52:55], v[208:211], v[216:219], v[52:55]
	v_mfma_f32_16x16x32_bf16 v[44:47], v[178:181], v[224:227], v[44:47]
	v_mfma_f32_16x16x32_bf16 v[36:39], v[208:211], v[224:227], v[36:39]
	v_mfma_f32_16x16x32_bf16 v[28:31], v[178:181], v[232:235], v[28:31]
	v_mfma_f32_16x16x32_bf16 v[20:23], v[208:211], v[232:235], v[20:23]
	v_mfma_f32_16x16x32_bf16 v[12:15], v[178:181], v[240:243], v[12:15]
	v_mfma_f32_16x16x32_bf16 v[4:7], v[208:211], v[240:243], v[4:7]
	s_setprio 3
	s_barrier
	s_add_i32 s60, s60, 2
	s_add_u32 s36, s36, 0x100
	s_addc_u32 s37, s37, 0
	s_add_u32 s58, s58, 0x100
	s_addc_u32 s59, s59, 0
	s_cmp_gt_u32 s60, 29
	s_cbranch_scc0 .LBB0_301
	s_and_b64 vcc, exec, s[8:9]
	s_cbranch_vccz .LBB0_304
	s_barrier

; #define PG8_STAGE(bufoff, gbase, voff) do { _Pragma("unroll") for (int _i = 0; _i < 2; ++_i) \
;         __builtin_amdgcn_global_load_lds((const unsigned*)((const char*)(gbase) + (voff)[_i]), (PG8_LAS unsigned*)(lds + (bufoff) + ldsw + _i * 8192), 16, 0, 0); } while (0)
; #define PG8_LDA(dst, b, h) do { _Pragma("unroll") for (int m = 0; m < 4; ++m) _Pragma("unroll") for (int k = 0; k < 2; ++k) dst[m][k] = *(const PG8_LAS bf16x8*)(lds + PG8_SA(b, h) + aoff + m * 2048 + k * 1024); } while (0)
; #define PG8_LDB(dst, b, h) do { _Pragma("unroll") for (int n = 0; n < 2; ++n) _Pragma("unroll") for (int k = 0; k < 2; ++k) dst[n][k] = *(const PG8_LAS bf16x8*)(lds + PG8_SB(b, h) + boff + n * 2048 + k * 1024); } while (0)
; #define PG8_MMA(ai, bj, At, Bt) do { __builtin_amdgcn_s_setprio(1); _Pragma("unroll") for (int m = 0; m < 4; ++m) _Pragma("unroll") for (int n = 0; n < 2; ++n) _Pragma("unroll") for (int k = 0; k < 2; ++k) \
;         acc[ai][bj][m][n] = __builtin_amdgcn_mfma_f32_16x16x32_bf16(Bt[n][k], At[m][k], acc[ai][bj][m][n], 0, 0, 0); __builtin_amdgcn_s_setprio(0); } while (0)
; #define PG8_WAIT_V(n) asm volatile("s_waitcnt vmcnt(" #n ")" ::: "memory")
; #define PG8_WAIT_L(n) asm volatile("s_waitcnt lgkmcnt(" #n ")" ::: "memory")
; #define PG8_BAR __builtin_amdgcn_s_barrier()
; template <class Epi, class Sched, bool ALIGN_EPI = false, bool SP2 = false>
; __device__ __forceinline__ void gemm_phase(PG8_LAS unsigned char* lds, const Gemm g, const Sched& S, const Epi& E) {
;     ...
;             const char* a1 = cA + (size_t)(t + 1) * kstep;
;             const char* a2 = last ? nA : cA + (size_t)(t + 2) * kstep; const char* b2 = last ? nB : cB + (size_t)(t + 2) * kstep;
;             const char* a3 = a2 + kstep; const char* b3 = b2 + kstep;
;             if (last && has_next) S.a_ready(nxt);
;             if constexpr (SP2) {
;             PG8_LDB(B0, 0, 0); PG8_LDB(B1, 0, 1); PG8_SCHED; PG8_LDA(At, 0, 0); PG8_STAGE(PG8_SA(1, 1), a1 + hstep, voffA);
;             PG8_WAIT_V(8); PG8_WAIT_L(0); PG8_BAR; PG8_MMA(0, 0, At, B0); PG8_MMA(0, 1, At, B1); PG8_BAR; PG8_SCHED;
;             PG8_LDA(At, 0, 1); PG8_STAGE(PG8_SB(0, 0), b2, voffB); PG8_STAGE(PG8_SB(0, 1), b2 + hstep, voffB); PG8_STAGE(PG8_SA(0, 0), a2, voffA);
;             PG8_WAIT_V(8); PG8_WAIT_L(0); PG8_BAR; PG8_MMA(1, 0, At, B0); PG8_MMA(1, 1, At, B1); PG8_BAR; PG8_SCHED;
.LBB0_575:
	s_add_u32 s36, s34, 0x100
	s_addc_u32 s37, s35, 0
	s_add_i32 s64, 0, 0x10000
	s_cmpk_eq_i32 s63, 0x52
	s_cselect_b32 s41, s5, s37
	s_cselect_b32 s40, s4, s36
	s_cselect_b32 s39, s31, s62
	s_cselect_b32 s38, s30, s61
	s_add_i32 s65, 0, 0x14000
	ds_read_b128 v[158:161], v247 offset:16384
	ds_read_b128 v[174:177], v247 offset:17408
	ds_read_b128 v[180:183], v247 offset:18432
	ds_read_b128 v[204:207], v247 offset:19456
	v_lshl_add_u64 v[162:163], s[34:35], 0, v[138:139]
	s_add_i32 m0, s47, 0xc000
	ds_read_b128 v[208:211], v179
	ds_read_b128 v[212:215], v179 offset:1024
	ds_read_b128 v[216:219], v179 offset:2048
	ds_read_b128 v[220:223], v179 offset:3072
	ds_read_b128 v[224:227], v179 offset:4096
	ds_read_b128 v[228:231], v179 offset:5120
	ds_read_b128 v[232:235], v179 offset:6144
	ds_read_b128 v[236:239], v179 offset:7168
	global_load_lds_dwordx4 v[162:163], off
	v_lshl_add_u64 v[162:163], s[34:35], 0, v[140:141]
	s_add_i32 m0, s47, 0xe000
	s_nop 0
	global_load_lds_dwordx4 v[162:163], off
	s_waitcnt vmcnt(8) lgkmcnt(0)
	s_setprio 0
	s_barrier
	v_mfma_f32_16x16x32_bf16 v[128:131], v[142:145], v[208:211], v[128:131]
	v_mfma_f32_16x16x32_bf16 v[124:127], v[150:153], v[208:211], v[124:127]
	v_mfma_f32_16x16x32_bf16 v[112:115], v[142:145], v[216:219], v[112:115]
	v_mfma_f32_16x16x32_bf16 v[108:111], v[150:153], v[216:219], v[108:111]
	v_mfma_f32_16x16x32_bf16 v[96:99], v[142:145], v[224:227], v[96:99]
	v_mfma_f32_16x16x32_bf16 v[92:95], v[150:153], v[224:227], v[92:95]
	v_mfma_f32_16x16x32_bf16 v[80:83], v[142:145], v[232:235], v[80:83]
	v_mfma_f32_16x16x32_bf16 v[76:79], v[150:153], v[232:235], v[76:79]
	v_mfma_f32_16x16x32_bf16 v[128:131], v[146:149], v[212:215], v[128:131]
	v_mfma_f32_16x16x32_bf16 v[124:127], v[154:157], v[212:215], v[124:127]
	v_mfma_f32_16x16x32_bf16 v[112:115], v[146:149], v[220:223], v[112:115]
	v_mfma_f32_16x16x32_bf16 v[108:111], v[154:157], v[220:223], v[108:111]
	v_mfma_f32_16x16x32_bf16 v[96:99], v[146:149], v[228:231], v[96:99]
	v_mfma_f32_16x16x32_bf16 v[92:95], v[154:157], v[228:231], v[92:95]
	v_mfma_f32_16x16x32_bf16 v[80:83], v[146:149], v[236:239], v[80:83]
	v_mfma_f32_16x16x32_bf16 v[76:79], v[154:157], v[236:239], v[76:79]
	v_mfma_f32_16x16x32_bf16 v[120:123], v[158:161], v[208:211], v[120:123]
	v_mfma_f32_16x16x32_bf16 v[116:119], v[180:183], v[208:211], v[116:119]
	v_mfma_f32_16x16x32_bf16 v[104:107], v[158:161], v[216:219], v[104:107]
	v_mfma_f32_16x16x32_bf16 v[100:103], v[180:183], v[216:219], v[100:103]
	v_mfma_f32_16x16x32_bf16 v[88:91], v[158:161], v[224:227], v[88:91]
	v_mfma_f32_16x16x32_bf16 v[84:87], v[180:183], v[224:227], v[84:87]
	v_mfma_f32_16x16x32_bf16 v[72:75], v[158:161], v[232:235], v[72:75]
	v_mfma_f32_16x16x32_bf16 v[68:71], v[180:183], v[232:235], v[68:71]
	v_mfma_f32_16x16x32_bf16 v[120:123], v[174:177], v[212:215], v[120:123]
	v_mfma_f32_16x16x32_bf16 v[116:119], v[204:207], v[212:215], v[116:119]
	v_mfma_f32_16x16x32_bf16 v[104:107], v[174:177], v[220:223], v[104:107]
	v_mfma_f32_16x16x32_bf16 v[100:103], v[204:207], v[220:223], v[100:103]
	v_mfma_f32_16x16x32_bf16 v[88:91], v[174:177], v[228:231], v[88:91]
	v_mfma_f32_16x16x32_bf16 v[84:87], v[204:207], v[228:231], v[84:87]
	v_mfma_f32_16x16x32_bf16 v[72:75], v[174:177], v[236:239], v[72:75]
	v_mfma_f32_16x16x32_bf16 v[68:71], v[204:207], v[236:239], v[68:71]
	s_setprio 3
	s_barrier
	s_add_i32 s34, s64, s46
	s_mov_b32 m0, s34
	ds_read_b128 v[208:211], v179 offset:16384
	ds_read_b128 v[212:215], v179 offset:17408
	ds_read_b128 v[216:219], v179 offset:18432
	ds_read_b128 v[220:223], v179 offset:19456
	ds_read_b128 v[224:227], v179 offset:20480
	ds_read_b128 v[228:231], v179 offset:21504
	ds_read_b128 v[232:235], v179 offset:22528
	ds_read_b128 v[236:239], v179 offset:23552
	global_load_lds_dwordx4 v2, s[38:39]
	s_add_i32 m0, s34, 0x2000
	s_add_u32 s34, s38, 0x158000
	s_addc_u32 s35, s39, 0
	s_add_i32 s64, s65, s46
	global_load_lds_dwordx4 v132, s[38:39]
	s_mov_b32 m0, s64
	s_nop 0
	global_load_lds_dwordx4 v2, s[34:35]
	s_add_i32 m0, s64, 0x2000
	s_nop 0
	global_load_lds_dwordx4 v132, s[34:35]
	s_mov_b32 m0, s47
	s_nop 0
	global_load_lds_dwordx4 v2, s[40:41]
	s_mov_b32 m0, s48
	s_nop 0
	global_load_lds_dwordx4 v132, s[40:41]
	s_waitcnt vmcnt(8) lgkmcnt(0)
	s_setprio 0
	s_barrier
	v_mfma_f32_16x16x32_bf16 v[64:67], v[142:145], v[208:211], v[64:67]
	v_mfma_f32_16x16x32_bf16 v[60:63], v[150:153], v[208:211], v[60:63]
	v_mfma_f32_16x16x32_bf16 v[48:51], v[142:145], v[216:219], v[48:51]
	v_mfma_f32_16x16x32_bf16 v[44:47], v[150:153], v[216:219], v[44:47]
	v_mfma_f32_16x16x32_bf16 v[32:35], v[142:145], v[224:227], v[32:35]
	v_mfma_f32_16x16x32_bf16 v[28:31], v[150:153], v[224:227], v[28:31]
	v_mfma_f32_16x16x32_bf16 v[16:19], v[142:145], v[232:235], v[16:19]
	v_mfma_f32_16x16x32_bf16 v[12:15], v[150:153], v[232:235], v[12:15]
	v_mfma_f32_16x16x32_bf16 v[64:67], v[146:149], v[212:215], v[64:67]
	v_mfma_f32_16x16x32_bf16 v[60:63], v[154:157], v[212:215], v[60:63]
	v_mfma_f32_16x16x32_bf16 v[48:51], v[146:149], v[220:223], v[48:51]
	v_mfma_f32_16x16x32_bf16 v[44:47], v[154:157], v[220:223], v[44:47]
	v_mfma_f32_16x16x32_bf16 v[32:35], v[146:149], v[228:231], v[32:35]
	v_mfma_f32_16x16x32_bf16 v[28:31], v[154:157], v[228:231], v[28:31]
	v_mfma_f32_16x16x32_bf16 v[16:19], v[146:149], v[236:239], v[16:19]
	v_mfma_f32_16x16x32_bf16 v[12:15], v[154:157], v[236:239], v[12:15]
	v_mfma_f32_16x16x32_bf16 v[56:59], v[158:161], v[208:211], v[56:59]
	ds_read_b128 v[142:145], v247 offset:32768
	v_mfma_f32_16x16x32_bf16 v[52:55], v[180:183], v[208:211], v[52:55]
	ds_read_b128 v[146:149], v247 offset:33792
	v_mfma_f32_16x16x32_bf16 v[40:43], v[158:161], v[216:219], v[40:43]
	ds_read_b128 v[150:153], v247 offset:34816
	v_mfma_f32_16x16x32_bf16 v[36:39], v[180:183], v[216:219], v[36:39]
	ds_read_b128 v[154:157], v247 offset:35840
	v_mfma_f32_16x16x32_bf16 v[24:27], v[158:161], v[224:227], v[24:27]
	v_mfma_f32_16x16x32_bf16 v[20:23], v[180:183], v[224:227], v[20:23]
	v_mfma_f32_16x16x32_bf16 v[8:11], v[158:161], v[232:235], v[8:11]
	v_mfma_f32_16x16x32_bf16 v[4:7], v[180:183], v[232:235], v[4:7]
	v_mfma_f32_16x16x32_bf16 v[56:59], v[174:177], v[212:215], v[56:59]
	v_mfma_f32_16x16x32_bf16 v[52:55], v[204:207], v[212:215], v[52:55]
	v_mfma_f32_16x16x32_bf16 v[40:43], v[174:177], v[220:223], v[40:43]
	v_mfma_f32_16x16x32_bf16 v[36:39], v[204:207], v[220:223], v[36:39]
	v_mfma_f32_16x16x32_bf16 v[24:27], v[174:177], v[228:231], v[24:27]
	v_mfma_f32_16x16x32_bf16 v[20:23], v[204:207], v[228:231], v[20:23]
	v_mfma_f32_16x16x32_bf16 v[8:11], v[174:177], v[236:239], v[8:11]
	v_mfma_f32_16x16x32_bf16 v[4:7], v[204:207], v[236:239], v[4:7]
	s_setprio 3
	s_barrier
; #define PG8_STAGE(bufoff, gbase, voff) do { _Pragma("unroll") for (int _i = 0; _i < 2; ++_i) \
;         __builtin_amdgcn_global_load_lds((const unsigned*)((const char*)(gbase) + (voff)[_i]), (PG8_LAS unsigned*)(lds + (bufoff) + ldsw + _i * 8192), 16, 0, 0); } while (0)
; #define PG8_LDA(dst, b, h) do { _Pragma("unroll") for (int m = 0; m < 4; ++m) _Pragma("unroll") for (int k = 0; k < 2; ++k) dst[m][k] = *(const PG8_LAS bf16x8*)(lds + PG8_SA(b, h) + aoff + m * 2048 + k * 1024); } while (0)
; #define PG8_LDB(dst, b, h) do { _Pragma("unroll") for (int n = 0; n < 2; ++n) _Pragma("unroll") for (int k = 0; k < 2; ++k) dst[n][k] = *(const PG8_LAS bf16x8*)(lds + PG8_SB(b, h) + boff + n * 2048 + k * 1024); } while (0)
; #define PG8_MMA(ai, bj, At, Bt) do { __builtin_amdgcn_s_setprio(1); _Pragma("unroll") for (int m = 0; m < 4; ++m) _Pragma("unroll") for (int n = 0; n < 2; ++n) _Pragma("unroll") for (int k = 0; k < 2; ++k) \
;         acc[ai][bj][m][n] = __builtin_amdgcn_mfma_f32_16x16x32_bf16(Bt[n][k], At[m][k], acc[ai][bj][m][n], 0, 0, 0); __builtin_amdgcn_s_setprio(0); } while (0)
; #define PG8_WAIT_V(n) asm volatile("s_waitcnt vmcnt(" #n ")" ::: "memory")
; #define PG8_WAIT_L(n) asm volatile("s_waitcnt lgkmcnt(" #n ")" ::: "memory")
; #define PG8_BAR __builtin_amdgcn_s_barrier()
; #define PG8_SCHED __builtin_amdgcn_sched_barrier(0)
; template <class Epi, class Sched, bool ALIGN_EPI = false, bool SP2 = false>
; __device__ __forceinline__ void gemm_phase(PG8_LAS unsigned char* lds, const Gemm g, const Sched& S, const Epi& E) {
;     ...
;             PG8_LDB(B0, 1, 0); PG8_LDB(B1, 1, 1); PG8_SCHED; PG8_LDA(At, 1, 0); PG8_STAGE(PG8_SA(0, 1), a2 + hstep, voffA);
;             PG8_WAIT_V(8); PG8_WAIT_L(0); PG8_BAR; PG8_MMA(0, 0, At, B0); PG8_MMA(0, 1, At, B1); PG8_BAR; PG8_SCHED;
;             PG8_LDA(At, 1, 1); PG8_STAGE(PG8_SB(1, 0), b3, voffB); PG8_STAGE(PG8_SB(1, 1), b3 + hstep, voffB); PG8_STAGE(PG8_SA(1, 0), a3, voffA);
;             PG8_WAIT_V(8); PG8_WAIT_L(0); PG8_BAR; PG8_MMA(1, 0, At, B0); PG8_MMA(1, 1, At, B1); PG8_BAR; PG8_SCHED;
	s_add_i32 s64, 0, 0x18000
	s_add_i32 s65, 0, 0x1c000
	ds_read_b128 v[158:161], v247 offset:49152
	ds_read_b128 v[174:177], v247 offset:50176
	ds_read_b128 v[180:183], v247 offset:51200
	ds_read_b128 v[204:207], v247 offset:52224
	s_add_u32 s34, s40, 0x158000
	s_addc_u32 s35, s41, 0
	s_mov_b32 m0, s49
	ds_read_b128 v[208:211], v179 offset:32768
	ds_read_b128 v[212:215], v179 offset:33792
	ds_read_b128 v[216:219], v179 offset:34816
	ds_read_b128 v[220:223], v179 offset:35840
	ds_read_b128 v[224:227], v179 offset:36864
	ds_read_b128 v[228:231], v179 offset:37888
	ds_read_b128 v[232:235], v179 offset:38912
	ds_read_b128 v[236:239], v179 offset:39936
	global_load_lds_dwordx4 v2, s[34:35]
	s_mov_b32 m0, s50
	s_nop 0
	global_load_lds_dwordx4 v132, s[34:35]
	s_nop 0
	s_waitcnt vmcnt(8) lgkmcnt(0)
	s_setprio 0
	s_barrier
	v_mfma_f32_16x16x32_bf16 v[128:131], v[142:145], v[208:211], v[128:131]
	v_mfma_f32_16x16x32_bf16 v[124:127], v[150:153], v[208:211], v[124:127]
	v_mfma_f32_16x16x32_bf16 v[112:115], v[142:145], v[216:219], v[112:115]
	v_mfma_f32_16x16x32_bf16 v[108:111], v[150:153], v[216:219], v[108:111]
	v_mfma_f32_16x16x32_bf16 v[96:99], v[142:145], v[224:227], v[96:99]
	v_mfma_f32_16x16x32_bf16 v[92:95], v[150:153], v[224:227], v[92:95]
	v_mfma_f32_16x16x32_bf16 v[80:83], v[142:145], v[232:235], v[80:83]
	v_mfma_f32_16x16x32_bf16 v[76:79], v[150:153], v[232:235], v[76:79]
	v_mfma_f32_16x16x32_bf16 v[128:131], v[146:149], v[212:215], v[128:131]
	v_mfma_f32_16x16x32_bf16 v[124:127], v[154:157], v[212:215], v[124:127]
	v_mfma_f32_16x16x32_bf16 v[112:115], v[146:149], v[220:223], v[112:115]
	v_mfma_f32_16x16x32_bf16 v[108:111], v[154:157], v[220:223], v[108:111]
	v_mfma_f32_16x16x32_bf16 v[96:99], v[146:149], v[228:231], v[96:99]
	v_mfma_f32_16x16x32_bf16 v[92:95], v[154:157], v[228:231], v[92:95]
	v_mfma_f32_16x16x32_bf16 v[80:83], v[146:149], v[236:239], v[80:83]
	v_mfma_f32_16x16x32_bf16 v[76:79], v[154:157], v[236:239], v[76:79]
	v_mfma_f32_16x16x32_bf16 v[120:123], v[158:161], v[208:211], v[120:123]
	v_mfma_f32_16x16x32_bf16 v[116:119], v[180:183], v[208:211], v[116:119]
	v_mfma_f32_16x16x32_bf16 v[104:107], v[158:161], v[216:219], v[104:107]
	v_mfma_f32_16x16x32_bf16 v[100:103], v[180:183], v[216:219], v[100:103]
	v_mfma_f32_16x16x32_bf16 v[88:91], v[158:161], v[224:227], v[88:91]
	v_mfma_f32_16x16x32_bf16 v[84:87], v[180:183], v[224:227], v[84:87]
	v_mfma_f32_16x16x32_bf16 v[72:75], v[158:161], v[232:235], v[72:75]
	v_mfma_f32_16x16x32_bf16 v[68:71], v[180:183], v[232:235], v[68:71]
	v_mfma_f32_16x16x32_bf16 v[120:123], v[174:177], v[212:215], v[120:123]
	v_mfma_f32_16x16x32_bf16 v[116:119], v[204:207], v[212:215], v[116:119]
	v_mfma_f32_16x16x32_bf16 v[104:107], v[174:177], v[220:223], v[104:107]
	v_mfma_f32_16x16x32_bf16 v[100:103], v[204:207], v[220:223], v[100:103]
	v_mfma_f32_16x16x32_bf16 v[88:91], v[174:177], v[228:231], v[88:91]
	v_mfma_f32_16x16x32_bf16 v[84:87], v[204:207], v[228:231], v[84:87]
	v_mfma_f32_16x16x32_bf16 v[72:75], v[174:177], v[236:239], v[72:75]
	v_mfma_f32_16x16x32_bf16 v[68:71], v[204:207], v[236:239], v[68:71]
	s_setprio 3
	s_barrier
	s_add_i32 s34, s64, s46
	s_add_i32 m0, s34, 0xffffff80
	ds_read_b128 v[208:211], v179 offset:49152
	ds_read_b128 v[212:215], v179 offset:50176
	ds_read_b128 v[216:219], v179 offset:51200
	ds_read_b128 v[220:223], v179 offset:52224
	ds_read_b128 v[224:227], v179 offset:53248
	ds_read_b128 v[228:231], v179 offset:54272
	ds_read_b128 v[232:235], v179 offset:55296
	ds_read_b128 v[236:239], v179 offset:56320
	global_load_lds_dwordx4 v2, s[38:39] offset:128
	s_add_i32 m0, s34, 0x1f80
	s_add_u32 s34, s38, 0x158080
	s_addc_u32 s35, s39, 0
	global_load_lds_dwordx4 v132, s[38:39] offset:128
	s_add_i32 s38, s65, s46
	s_mov_b32 m0, s38
	s_nop 0
	global_load_lds_dwordx4 v2, s[34:35]
	s_add_i32 m0, s38, 0x2000
	s_nop 0
	global_load_lds_dwordx4 v132, s[34:35]
	s_add_i32 m0, s53, 0xffffff80
	s_nop 0
	global_load_lds_dwordx4 v2, s[40:41] offset:128
	s_add_i32 m0, s54, 0xffffff80
	s_nop 0
	global_load_lds_dwordx4 v132, s[40:41] offset:128
	s_nop 0
	s_waitcnt vmcnt(8) lgkmcnt(0)
	s_setprio 0
	s_barrier
	v_mfma_f32_16x16x32_bf16 v[64:67], v[142:145], v[208:211], v[64:67]
	v_mfma_f32_16x16x32_bf16 v[60:63], v[150:153], v[208:211], v[60:63]
	v_mfma_f32_16x16x32_bf16 v[48:51], v[142:145], v[216:219], v[48:51]
	v_mfma_f32_16x16x32_bf16 v[44:47], v[150:153], v[216:219], v[44:47]
	v_mfma_f32_16x16x32_bf16 v[32:35], v[142:145], v[224:227], v[32:35]
	v_mfma_f32_16x16x32_bf16 v[28:31], v[150:153], v[224:227], v[28:31]
	v_mfma_f32_16x16x32_bf16 v[16:19], v[142:145], v[232:235], v[16:19]
	v_mfma_f32_16x16x32_bf16 v[12:15], v[150:153], v[232:235], v[12:15]
	v_mfma_f32_16x16x32_bf16 v[64:67], v[146:149], v[212:215], v[64:67]
	v_mfma_f32_16x16x32_bf16 v[60:63], v[154:157], v[212:215], v[60:63]
	v_mfma_f32_16x16x32_bf16 v[48:51], v[146:149], v[220:223], v[48:51]
	v_mfma_f32_16x16x32_bf16 v[44:47], v[154:157], v[220:223], v[44:47]
	v_mfma_f32_16x16x32_bf16 v[32:35], v[146:149], v[228:231], v[32:35]
	v_mfma_f32_16x16x32_bf16 v[28:31], v[154:157], v[228:231], v[28:31]
	v_mfma_f32_16x16x32_bf16 v[16:19], v[146:149], v[236:239], v[16:19]
	v_mfma_f32_16x16x32_bf16 v[12:15], v[154:157], v[236:239], v[12:15]
	v_mfma_f32_16x16x32_bf16 v[56:59], v[158:161], v[208:211], v[56:59]
	ds_read_b128 v[142:145], v247
	v_mfma_f32_16x16x32_bf16 v[52:55], v[180:183], v[208:211], v[52:55]
	ds_read_b128 v[146:149], v247 offset:1024
	v_mfma_f32_16x16x32_bf16 v[40:43], v[158:161], v[216:219], v[40:43]
	ds_read_b128 v[150:153], v247 offset:2048
	v_mfma_f32_16x16x32_bf16 v[36:39], v[180:183], v[216:219], v[36:39]
	ds_read_b128 v[154:157], v247 offset:3072
	v_mfma_f32_16x16x32_bf16 v[24:27], v[158:161], v[224:227], v[24:27]
	v_mfma_f32_16x16x32_bf16 v[20:23], v[180:183], v[224:227], v[20:23]
	v_mfma_f32_16x16x32_bf16 v[8:11], v[158:161], v[232:235], v[8:11]
	v_mfma_f32_16x16x32_bf16 v[4:7], v[180:183], v[232:235], v[4:7]
	v_mfma_f32_16x16x32_bf16 v[56:59], v[174:177], v[212:215], v[56:59]
	v_mfma_f32_16x16x32_bf16 v[52:55], v[204:207], v[212:215], v[52:55]
	v_mfma_f32_16x16x32_bf16 v[40:43], v[174:177], v[220:223], v[40:43]
	v_mfma_f32_16x16x32_bf16 v[36:39], v[204:207], v[220:223], v[36:39]
	v_mfma_f32_16x16x32_bf16 v[24:27], v[174:177], v[228:231], v[24:27]
	v_mfma_f32_16x16x32_bf16 v[20:23], v[204:207], v[228:231], v[20:23]
	v_mfma_f32_16x16x32_bf16 v[8:11], v[174:177], v[236:239], v[8:11]
	v_mfma_f32_16x16x32_bf16 v[4:7], v[204:207], v[236:239], v[4:7]
	s_setprio 3
	s_barrier
	s_add_i32 s63, s63, 2
	s_add_u32 s61, s61, 0x100
	s_addc_u32 s62, s62, 0
	s_cmpk_gt_u32 s63, 0x53
	s_mov_b64 s[34:35], s[36:37]
	s_cbranch_scc0 .LBB0_575
	s_and_b64 vcc, exec, s[28:29]
	s_cbranch_vccz .LBB0_578
	s_barrier

; #define PG8_STAGE(bufoff, gbase, voff) do { _Pragma("unroll") for (int _i = 0; _i < 2; ++_i) \
;         __builtin_amdgcn_global_load_lds((const unsigned*)((const char*)(gbase) + (voff)[_i]), (PG8_LAS unsigned*)(lds + (bufoff) + ldsw + _i * 8192), 16, 0, 0); } while (0)
; #define PG8_LDA(dst, b, h) do { _Pragma("unroll") for (int m = 0; m < 4; ++m) _Pragma("unroll") for (int k = 0; k < 2; ++k) dst[m][k] = *(const PG8_LAS bf16x8*)(lds + PG8_SA(b, h) + aoff + m * 2048 + k * 1024); } while (0)
; #define PG8_LDB(dst, b, h) do { _Pragma("unroll") for (int n = 0; n < 2; ++n) _Pragma("unroll") for (int k = 0; k < 2; ++k) dst[n][k] = *(const PG8_LAS bf16x8*)(lds + PG8_SB(b, h) + boff + n * 2048 + k * 1024); } while (0)
; #define PG8_MMA(ai, bj, At, Bt) do { __builtin_amdgcn_s_setprio(1); _Pragma("unroll") for (int m = 0; m < 4; ++m) _Pragma("unroll") for (int n = 0; n < 2; ++n) _Pragma("unroll") for (int k = 0; k < 2; ++k) \
;         acc[ai][bj][m][n] = __builtin_amdgcn_mfma_f32_16x16x32_bf16(Bt[n][k], At[m][k], acc[ai][bj][m][n], 0, 0, 0); __builtin_amdgcn_s_setprio(0); } while (0)
; #define PG8_WAIT_V(n) asm volatile("s_waitcnt vmcnt(" #n ")" ::: "memory")
; #define PG8_WAIT_L(n) asm volatile("s_waitcnt lgkmcnt(" #n ")" ::: "memory")
; #define PG8_BAR __builtin_amdgcn_s_barrier()
; template <class Epi, class Sched, bool ALIGN_EPI = false, bool SP2 = false>
; __device__ __forceinline__ void gemm_phase(PG8_LAS unsigned char* lds, const Gemm g, const Sched& S, const Epi& E) {
;     ...
;             const char* a1 = cA + (size_t)(t + 1) * kstep;
;             const char* a2 = last ? nA : cA + (size_t)(t + 2) * kstep; const char* b2 = last ? nB : cB + (size_t)(t + 2) * kstep;
;             const char* a3 = a2 + kstep; const char* b3 = b2 + kstep;
;             if (last && has_next) S.a_ready(nxt);
;             if constexpr (SP2) {
;             PG8_LDB(B0, 0, 0); PG8_LDB(B1, 0, 1); PG8_SCHED; PG8_LDA(At, 0, 0); PG8_STAGE(PG8_SA(1, 1), a1 + hstep, voffA);
;             PG8_WAIT_V(8); PG8_WAIT_L(0); PG8_BAR; PG8_MMA(0, 0, At, B0); PG8_MMA(0, 1, At, B1); PG8_BAR; PG8_SCHED;
;             PG8_LDA(At, 0, 1); PG8_STAGE(PG8_SB(0, 0), b2, voffB); PG8_STAGE(PG8_SB(0, 1), b2 + hstep, voffB); PG8_STAGE(PG8_SA(0, 0), a2, voffA);
;             PG8_WAIT_V(8); PG8_WAIT_L(0); PG8_BAR; PG8_MMA(1, 0, At, B0); PG8_MMA(1, 1, At, B1); PG8_BAR; PG8_SCHED;
.LBB0_674:
	s_add_u32 s42, s40, 0xfff80080
	s_addc_u32 s43, s41, -1
	s_add_i32 s64, 0, 0x10000
	s_cmp_eq_u32 s63, 28
	s_cselect_b32 s45, s5, s43
	s_cselect_b32 s44, s4, s42
	s_cselect_b32 s43, s37, s62
	s_cselect_b32 s42, s36, s35
	s_add_i32 s66, 0, 0x14000
	ds_read_b128 v[158:161], v249 offset:16384
	ds_read_b128 v[174:177], v249 offset:17408
	ds_read_b128 v[206:209], v249 offset:18432
	ds_read_b128 v[210:213], v249 offset:19456
	s_add_i32 m0, s39, 0xc000
	ds_read_b128 v[214:217], v204
	ds_read_b128 v[218:221], v204 offset:1024
	ds_read_b128 v[222:225], v204 offset:2048
	ds_read_b128 v[226:229], v204 offset:3072
	ds_read_b128 v[230:233], v204 offset:4096
	ds_read_b128 v[234:237], v204 offset:5120
	ds_read_b128 v[238:241], v204 offset:6144
	ds_read_b128 v[242:245], v204 offset:7168
	global_load_lds_dwordx4 v154, s[40:41]
	s_add_i32 m0, s39, 0xe000
	s_nop 0
	global_load_lds_dwordx4 v156, s[40:41]
	s_waitcnt vmcnt(8) lgkmcnt(0)
	s_setprio 0
	s_barrier
	v_mfma_f32_16x16x32_bf16 v[128:131], v[132:135], v[214:217], v[128:131]
	v_mfma_f32_16x16x32_bf16 v[124:127], v[140:143], v[214:217], v[124:127]
	v_mfma_f32_16x16x32_bf16 v[116:119], v[132:135], v[222:225], v[116:119]
	v_mfma_f32_16x16x32_bf16 v[108:111], v[140:143], v[222:225], v[108:111]
	v_mfma_f32_16x16x32_bf16 v[100:103], v[132:135], v[230:233], v[100:103]
	v_mfma_f32_16x16x32_bf16 v[92:95], v[140:143], v[230:233], v[92:95]
	v_mfma_f32_16x16x32_bf16 v[84:87], v[132:135], v[238:241], v[84:87]
	v_mfma_f32_16x16x32_bf16 v[76:79], v[140:143], v[238:241], v[76:79]
	v_mfma_f32_16x16x32_bf16 v[128:131], v[136:139], v[218:221], v[128:131]
	v_mfma_f32_16x16x32_bf16 v[124:127], v[144:147], v[218:221], v[124:127]
	v_mfma_f32_16x16x32_bf16 v[116:119], v[136:139], v[226:229], v[116:119]
	v_mfma_f32_16x16x32_bf16 v[108:111], v[144:147], v[226:229], v[108:111]
	v_mfma_f32_16x16x32_bf16 v[100:103], v[136:139], v[234:237], v[100:103]
	v_mfma_f32_16x16x32_bf16 v[92:95], v[144:147], v[234:237], v[92:95]
	v_mfma_f32_16x16x32_bf16 v[84:87], v[136:139], v[242:245], v[84:87]
	v_mfma_f32_16x16x32_bf16 v[76:79], v[144:147], v[242:245], v[76:79]
	v_mfma_f32_16x16x32_bf16 v[120:123], v[158:161], v[214:217], v[120:123]
	v_mfma_f32_16x16x32_bf16 v[112:115], v[206:209], v[214:217], v[112:115]
	v_mfma_f32_16x16x32_bf16 v[104:107], v[158:161], v[222:225], v[104:107]
	v_mfma_f32_16x16x32_bf16 v[96:99], v[206:209], v[222:225], v[96:99]
	v_mfma_f32_16x16x32_bf16 v[88:91], v[158:161], v[230:233], v[88:91]
	v_mfma_f32_16x16x32_bf16 v[80:83], v[206:209], v[230:233], v[80:83]
	v_mfma_f32_16x16x32_bf16 v[72:75], v[158:161], v[238:241], v[72:75]
	v_mfma_f32_16x16x32_bf16 v[68:71], v[206:209], v[238:241], v[68:71]
	v_mfma_f32_16x16x32_bf16 v[120:123], v[174:177], v[218:221], v[120:123]
	v_mfma_f32_16x16x32_bf16 v[112:115], v[210:213], v[218:221], v[112:115]
	v_mfma_f32_16x16x32_bf16 v[104:107], v[174:177], v[226:229], v[104:107]
	v_mfma_f32_16x16x32_bf16 v[96:99], v[210:213], v[226:229], v[96:99]
	v_mfma_f32_16x16x32_bf16 v[88:91], v[174:177], v[234:237], v[88:91]
	v_mfma_f32_16x16x32_bf16 v[80:83], v[210:213], v[234:237], v[80:83]
	v_mfma_f32_16x16x32_bf16 v[72:75], v[174:177], v[242:245], v[72:75]
	v_mfma_f32_16x16x32_bf16 v[68:71], v[210:213], v[242:245], v[68:71]
	s_setprio 3
	s_barrier
	s_add_i32 s64, s64, s46
	s_mov_b32 m0, s64
	ds_read_b128 v[214:217], v204 offset:16384
	ds_read_b128 v[218:221], v204 offset:17408
	ds_read_b128 v[222:225], v204 offset:18432
	ds_read_b128 v[226:229], v204 offset:19456
	ds_read_b128 v[230:233], v204 offset:20480
	ds_read_b128 v[234:237], v204 offset:21504
	ds_read_b128 v[238:241], v204 offset:22528
	ds_read_b128 v[242:245], v204 offset:23552
	global_load_lds_dwordx4 v2, s[42:43]
	s_add_i32 m0, s64, 0x2000
	s_add_u32 s64, s42, 0x80000
	s_addc_u32 s65, s43, 0
	s_add_i32 s66, s66, s46
	global_load_lds_dwordx4 v148, s[42:43]
	s_mov_b32 m0, s66
	s_nop 0
	global_load_lds_dwordx4 v2, s[64:65]
	s_add_i32 m0, s66, 0x2000
	s_nop 0
	global_load_lds_dwordx4 v148, s[64:65]
	s_mov_b32 m0, s39
	s_nop 0
	global_load_lds_dwordx4 v152, s[44:45]
	s_mov_b32 m0, s51
	s_nop 0
	global_load_lds_dwordx4 v150, s[44:45]
	s_waitcnt vmcnt(8) lgkmcnt(0)
	s_setprio 0
	s_barrier
	v_mfma_f32_16x16x32_bf16 v[64:67], v[132:135], v[214:217], v[64:67]
	v_mfma_f32_16x16x32_bf16 v[60:63], v[140:143], v[214:217], v[60:63]
	v_mfma_f32_16x16x32_bf16 v[52:55], v[132:135], v[222:225], v[52:55]
	v_mfma_f32_16x16x32_bf16 v[44:47], v[140:143], v[222:225], v[44:47]
	v_mfma_f32_16x16x32_bf16 v[36:39], v[132:135], v[230:233], v[36:39]
	v_mfma_f32_16x16x32_bf16 v[28:31], v[140:143], v[230:233], v[28:31]
	v_mfma_f32_16x16x32_bf16 v[20:23], v[132:135], v[238:241], v[20:23]
	v_mfma_f32_16x16x32_bf16 v[12:15], v[140:143], v[238:241], v[12:15]
	v_mfma_f32_16x16x32_bf16 v[64:67], v[136:139], v[218:221], v[64:67]
	v_mfma_f32_16x16x32_bf16 v[60:63], v[144:147], v[218:221], v[60:63]
	v_mfma_f32_16x16x32_bf16 v[52:55], v[136:139], v[226:229], v[52:55]
	v_mfma_f32_16x16x32_bf16 v[44:47], v[144:147], v[226:229], v[44:47]
	v_mfma_f32_16x16x32_bf16 v[36:39], v[136:139], v[234:237], v[36:39]
	v_mfma_f32_16x16x32_bf16 v[28:31], v[144:147], v[234:237], v[28:31]
	v_mfma_f32_16x16x32_bf16 v[20:23], v[136:139], v[242:245], v[20:23]
	v_mfma_f32_16x16x32_bf16 v[12:15], v[144:147], v[242:245], v[12:15]
	v_mfma_f32_16x16x32_bf16 v[56:59], v[158:161], v[214:217], v[56:59]
	ds_read_b128 v[132:135], v249 offset:32768
	v_mfma_f32_16x16x32_bf16 v[48:51], v[206:209], v[214:217], v[48:51]
	ds_read_b128 v[136:139], v249 offset:33792
	v_mfma_f32_16x16x32_bf16 v[40:43], v[158:161], v[222:225], v[40:43]
	ds_read_b128 v[140:143], v249 offset:34816
	v_mfma_f32_16x16x32_bf16 v[32:35], v[206:209], v[222:225], v[32:35]
	ds_read_b128 v[144:147], v249 offset:35840
	v_mfma_f32_16x16x32_bf16 v[24:27], v[158:161], v[230:233], v[24:27]
	v_mfma_f32_16x16x32_bf16 v[16:19], v[206:209], v[230:233], v[16:19]
	v_mfma_f32_16x16x32_bf16 v[8:11], v[158:161], v[238:241], v[8:11]
	v_mfma_f32_16x16x32_bf16 v[4:7], v[206:209], v[238:241], v[4:7]
	v_mfma_f32_16x16x32_bf16 v[56:59], v[174:177], v[218:221], v[56:59]
	v_mfma_f32_16x16x32_bf16 v[48:51], v[210:213], v[218:221], v[48:51]
	v_mfma_f32_16x16x32_bf16 v[40:43], v[174:177], v[226:229], v[40:43]
	v_mfma_f32_16x16x32_bf16 v[32:35], v[210:213], v[226:229], v[32:35]
	v_mfma_f32_16x16x32_bf16 v[24:27], v[174:177], v[234:237], v[24:27]
	v_mfma_f32_16x16x32_bf16 v[16:19], v[210:213], v[234:237], v[16:19]
	v_mfma_f32_16x16x32_bf16 v[8:11], v[174:177], v[242:245], v[8:11]
	v_mfma_f32_16x16x32_bf16 v[4:7], v[210:213], v[242:245], v[4:7]
	s_setprio 3
	s_barrier
; #define PG8_STAGE(bufoff, gbase, voff) do { _Pragma("unroll") for (int _i = 0; _i < 2; ++_i) \
;         __builtin_amdgcn_global_load_lds((const unsigned*)((const char*)(gbase) + (voff)[_i]), (PG8_LAS unsigned*)(lds + (bufoff) + ldsw + _i * 8192), 16, 0, 0); } while (0)
; #define PG8_LDA(dst, b, h) do { _Pragma("unroll") for (int m = 0; m < 4; ++m) _Pragma("unroll") for (int k = 0; k < 2; ++k) dst[m][k] = *(const PG8_LAS bf16x8*)(lds + PG8_SA(b, h) + aoff + m * 2048 + k * 1024); } while (0)
; #define PG8_LDB(dst, b, h) do { _Pragma("unroll") for (int n = 0; n < 2; ++n) _Pragma("unroll") for (int k = 0; k < 2; ++k) dst[n][k] = *(const PG8_LAS bf16x8*)(lds + PG8_SB(b, h) + boff + n * 2048 + k * 1024); } while (0)
; #define PG8_MMA(ai, bj, At, Bt) do { __builtin_amdgcn_s_setprio(1); _Pragma("unroll") for (int m = 0; m < 4; ++m) _Pragma("unroll") for (int n = 0; n < 2; ++n) _Pragma("unroll") for (int k = 0; k < 2; ++k) \
;         acc[ai][bj][m][n] = __builtin_amdgcn_mfma_f32_16x16x32_bf16(Bt[n][k], At[m][k], acc[ai][bj][m][n], 0, 0, 0); __builtin_amdgcn_s_setprio(0); } while (0)
; #define PG8_WAIT_V(n) asm volatile("s_waitcnt vmcnt(" #n ")" ::: "memory")
; #define PG8_WAIT_L(n) asm volatile("s_waitcnt lgkmcnt(" #n ")" ::: "memory")
; #define PG8_BAR __builtin_amdgcn_s_barrier()
; #define PG8_SCHED __builtin_amdgcn_sched_barrier(0)
; template <class Epi, class Sched, bool ALIGN_EPI = false, bool SP2 = false>
; __device__ __forceinline__ void gemm_phase(PG8_LAS unsigned char* lds, const Gemm g, const Sched& S, const Epi& E) {
;     ...
;             PG8_LDB(B0, 1, 0); PG8_LDB(B1, 1, 1); PG8_SCHED; PG8_LDA(At, 1, 0); PG8_STAGE(PG8_SA(0, 1), a2 + hstep, voffA);
;             PG8_WAIT_V(8); PG8_WAIT_L(0); PG8_BAR; PG8_MMA(0, 0, At, B0); PG8_MMA(0, 1, At, B1); PG8_BAR; PG8_SCHED;
;             PG8_LDA(At, 1, 1); PG8_STAGE(PG8_SB(1, 0), b3, voffB); PG8_STAGE(PG8_SB(1, 1), b3 + hstep, voffB); PG8_STAGE(PG8_SA(1, 0), a3, voffA);
;             PG8_WAIT_V(8); PG8_WAIT_L(0); PG8_BAR; PG8_MMA(1, 0, At, B0); PG8_MMA(1, 1, At, B1); PG8_BAR; PG8_SCHED;
	s_add_i32 s64, 0, 0x18000
	s_add_i32 s65, 0, 0x1c000
	ds_read_b128 v[158:161], v249 offset:49152
	ds_read_b128 v[174:177], v249 offset:50176
	ds_read_b128 v[206:209], v249 offset:51200
	ds_read_b128 v[210:213], v249 offset:52224
	s_add_u32 s100, s44, 0x80
	s_addc_u32 s101, s45, 0
	s_add_u32 s44, s44, 0x80000
	s_addc_u32 s45, s45, 0
	s_mov_b32 m0, s52
	ds_read_b128 v[214:217], v204 offset:32768
	ds_read_b128 v[218:221], v204 offset:33792
	ds_read_b128 v[222:225], v204 offset:34816
	ds_read_b128 v[226:229], v204 offset:35840
	ds_read_b128 v[230:233], v204 offset:36864
	ds_read_b128 v[234:237], v204 offset:37888
	ds_read_b128 v[238:241], v204 offset:38912
	ds_read_b128 v[242:245], v204 offset:39936
	global_load_lds_dwordx4 v152, s[44:45]
	s_mov_b32 m0, s53
	s_nop 0
	global_load_lds_dwordx4 v150, s[44:45]
	s_waitcnt vmcnt(8) lgkmcnt(0)
	s_setprio 0
	s_barrier
	v_mfma_f32_16x16x32_bf16 v[128:131], v[132:135], v[214:217], v[128:131]
	v_mfma_f32_16x16x32_bf16 v[124:127], v[140:143], v[214:217], v[124:127]
	v_mfma_f32_16x16x32_bf16 v[116:119], v[132:135], v[222:225], v[116:119]
	v_mfma_f32_16x16x32_bf16 v[108:111], v[140:143], v[222:225], v[108:111]
	v_mfma_f32_16x16x32_bf16 v[100:103], v[132:135], v[230:233], v[100:103]
	v_mfma_f32_16x16x32_bf16 v[92:95], v[140:143], v[230:233], v[92:95]
	v_mfma_f32_16x16x32_bf16 v[84:87], v[132:135], v[238:241], v[84:87]
	v_mfma_f32_16x16x32_bf16 v[76:79], v[140:143], v[238:241], v[76:79]
	v_mfma_f32_16x16x32_bf16 v[128:131], v[136:139], v[218:221], v[128:131]
	v_mfma_f32_16x16x32_bf16 v[124:127], v[144:147], v[218:221], v[124:127]
	v_mfma_f32_16x16x32_bf16 v[116:119], v[136:139], v[226:229], v[116:119]
	v_mfma_f32_16x16x32_bf16 v[108:111], v[144:147], v[226:229], v[108:111]
	v_mfma_f32_16x16x32_bf16 v[100:103], v[136:139], v[234:237], v[100:103]
	v_mfma_f32_16x16x32_bf16 v[92:95], v[144:147], v[234:237], v[92:95]
	v_mfma_f32_16x16x32_bf16 v[84:87], v[136:139], v[242:245], v[84:87]
	v_mfma_f32_16x16x32_bf16 v[76:79], v[144:147], v[242:245], v[76:79]
	v_mfma_f32_16x16x32_bf16 v[120:123], v[158:161], v[214:217], v[120:123]
	v_mfma_f32_16x16x32_bf16 v[112:115], v[206:209], v[214:217], v[112:115]
	v_mfma_f32_16x16x32_bf16 v[104:107], v[158:161], v[222:225], v[104:107]
	v_mfma_f32_16x16x32_bf16 v[96:99], v[206:209], v[222:225], v[96:99]
	v_mfma_f32_16x16x32_bf16 v[88:91], v[158:161], v[230:233], v[88:91]
	v_mfma_f32_16x16x32_bf16 v[80:83], v[206:209], v[230:233], v[80:83]
	v_mfma_f32_16x16x32_bf16 v[72:75], v[158:161], v[238:241], v[72:75]
	v_mfma_f32_16x16x32_bf16 v[68:71], v[206:209], v[238:241], v[68:71]
	v_mfma_f32_16x16x32_bf16 v[120:123], v[174:177], v[218:221], v[120:123]
	v_mfma_f32_16x16x32_bf16 v[112:115], v[210:213], v[218:221], v[112:115]
	v_mfma_f32_16x16x32_bf16 v[104:107], v[174:177], v[226:229], v[104:107]
	v_mfma_f32_16x16x32_bf16 v[96:99], v[210:213], v[226:229], v[96:99]
	v_mfma_f32_16x16x32_bf16 v[88:91], v[174:177], v[234:237], v[88:91]
	v_mfma_f32_16x16x32_bf16 v[80:83], v[210:213], v[234:237], v[80:83]
	v_mfma_f32_16x16x32_bf16 v[72:75], v[174:177], v[242:245], v[72:75]
	v_mfma_f32_16x16x32_bf16 v[68:71], v[210:213], v[242:245], v[68:71]
	s_setprio 3
	s_barrier
	s_add_i32 s44, s64, s46
	s_add_i32 m0, s44, 0xffffff80
	ds_read_b128 v[214:217], v204 offset:49152
	ds_read_b128 v[218:221], v204 offset:50176
	ds_read_b128 v[222:225], v204 offset:51200
	ds_read_b128 v[226:229], v204 offset:52224
	ds_read_b128 v[230:233], v204 offset:53248
	ds_read_b128 v[234:237], v204 offset:54272
	ds_read_b128 v[238:241], v204 offset:55296
	ds_read_b128 v[242:245], v204 offset:56320
	global_load_lds_dwordx4 v2, s[42:43] offset:128
	s_add_i32 m0, s44, 0x1f80
	s_add_i32 s44, s65, s46
	global_load_lds_dwordx4 v148, s[42:43] offset:128
	s_add_u32 s42, s42, 0x80080
	s_addc_u32 s43, s43, 0
	s_mov_b32 m0, s44
	s_nop 0
	global_load_lds_dwordx4 v2, s[42:43]
	s_add_i32 m0, s44, 0x2000
	s_nop 0
	global_load_lds_dwordx4 v148, s[42:43]
	s_mov_b32 m0, s54
	s_nop 0
	global_load_lds_dwordx4 v152, s[100:101]
	s_mov_b32 m0, s55
	s_nop 0
	global_load_lds_dwordx4 v150, s[100:101]
	s_nop 0
	s_waitcnt vmcnt(8) lgkmcnt(0)
	s_setprio 0
	s_barrier
	v_mfma_f32_16x16x32_bf16 v[64:67], v[132:135], v[214:217], v[64:67]
	v_mfma_f32_16x16x32_bf16 v[60:63], v[140:143], v[214:217], v[60:63]
	v_mfma_f32_16x16x32_bf16 v[52:55], v[132:135], v[222:225], v[52:55]
	v_mfma_f32_16x16x32_bf16 v[44:47], v[140:143], v[222:225], v[44:47]
	v_mfma_f32_16x16x32_bf16 v[36:39], v[132:135], v[230:233], v[36:39]
	v_mfma_f32_16x16x32_bf16 v[28:31], v[140:143], v[230:233], v[28:31]
	v_mfma_f32_16x16x32_bf16 v[20:23], v[132:135], v[238:241], v[20:23]
	v_mfma_f32_16x16x32_bf16 v[12:15], v[140:143], v[238:241], v[12:15]
	v_mfma_f32_16x16x32_bf16 v[64:67], v[136:139], v[218:221], v[64:67]
	v_mfma_f32_16x16x32_bf16 v[60:63], v[144:147], v[218:221], v[60:63]
	v_mfma_f32_16x16x32_bf16 v[52:55], v[136:139], v[226:229], v[52:55]
	v_mfma_f32_16x16x32_bf16 v[44:47], v[144:147], v[226:229], v[44:47]
	v_mfma_f32_16x16x32_bf16 v[36:39], v[136:139], v[234:237], v[36:39]
	v_mfma_f32_16x16x32_bf16 v[28:31], v[144:147], v[234:237], v[28:31]
	v_mfma_f32_16x16x32_bf16 v[20:23], v[136:139], v[242:245], v[20:23]
	v_mfma_f32_16x16x32_bf16 v[12:15], v[144:147], v[242:245], v[12:15]
	v_mfma_f32_16x16x32_bf16 v[56:59], v[158:161], v[214:217], v[56:59]
	ds_read_b128 v[132:135], v249
	v_mfma_f32_16x16x32_bf16 v[48:51], v[206:209], v[214:217], v[48:51]
	ds_read_b128 v[136:139], v249 offset:1024
	v_mfma_f32_16x16x32_bf16 v[40:43], v[158:161], v[222:225], v[40:43]
	ds_read_b128 v[140:143], v249 offset:2048
	v_mfma_f32_16x16x32_bf16 v[32:35], v[206:209], v[222:225], v[32:35]
	ds_read_b128 v[144:147], v249 offset:3072
	v_mfma_f32_16x16x32_bf16 v[24:27], v[158:161], v[230:233], v[24:27]
	v_mfma_f32_16x16x32_bf16 v[16:19], v[206:209], v[230:233], v[16:19]
	v_mfma_f32_16x16x32_bf16 v[8:11], v[158:161], v[238:241], v[8:11]
	v_mfma_f32_16x16x32_bf16 v[4:7], v[206:209], v[238:241], v[4:7]
	v_mfma_f32_16x16x32_bf16 v[56:59], v[174:177], v[218:221], v[56:59]
	v_mfma_f32_16x16x32_bf16 v[48:51], v[210:213], v[218:221], v[48:51]
	v_mfma_f32_16x16x32_bf16 v[40:43], v[174:177], v[226:229], v[40:43]
	v_mfma_f32_16x16x32_bf16 v[32:35], v[210:213], v[226:229], v[32:35]
	v_mfma_f32_16x16x32_bf16 v[24:27], v[174:177], v[234:237], v[24:27]
	v_mfma_f32_16x16x32_bf16 v[16:19], v[210:213], v[234:237], v[16:19]
	v_mfma_f32_16x16x32_bf16 v[8:11], v[174:177], v[242:245], v[8:11]
	v_mfma_f32_16x16x32_bf16 v[4:7], v[210:213], v[242:245], v[4:7]
	s_setprio 3
	s_barrier
	s_add_i32 s63, s63, 2
	s_add_u32 s40, s40, 0x100
	s_addc_u32 s41, s41, 0
	s_add_u32 s35, s35, 0x100
	s_addc_u32 s62, s62, 0
	s_cmp_gt_u32 s63, 29
	s_cbranch_scc0 .LBB0_674
	s_and_b64 vcc, exec, s[30:31]
	s_cbranch_vccz .LBB0_677
	s_barrier

; #define PG8_STAGE(bufoff, gbase, voff) do { _Pragma("unroll") for (int _i = 0; _i < 2; ++_i) \
;         __builtin_amdgcn_global_load_lds((const unsigned*)((const char*)(gbase) + (voff)[_i]), (PG8_LAS unsigned*)(lds + (bufoff) + ldsw + _i * 8192), 16, 0, 0); } while (0)
; #define PG8_LDA(dst, b, h) do { _Pragma("unroll") for (int m = 0; m < 4; ++m) _Pragma("unroll") for (int k = 0; k < 2; ++k) dst[m][k] = *(const PG8_LAS bf16x8*)(lds + PG8_SA(b, h) + aoff + m * 2048 + k * 1024); } while (0)
; #define PG8_LDB(dst, b, h) do { _Pragma("unroll") for (int n = 0; n < 2; ++n) _Pragma("unroll") for (int k = 0; k < 2; ++k) dst[n][k] = *(const PG8_LAS bf16x8*)(lds + PG8_SB(b, h) + boff + n * 2048 + k * 1024); } while (0)
; #define PG8_MMA(ai, bj, At, Bt) do { __builtin_amdgcn_s_setprio(1); _Pragma("unroll") for (int m = 0; m < 4; ++m) _Pragma("unroll") for (int n = 0; n < 2; ++n) _Pragma("unroll") for (int k = 0; k < 2; ++k) \
;         acc[ai][bj][m][n] = __builtin_amdgcn_mfma_f32_16x16x32_bf16(Bt[n][k], At[m][k], acc[ai][bj][m][n], 0, 0, 0); __builtin_amdgcn_s_setprio(0); } while (0)
; #define PG8_WAIT_V(n) asm volatile("s_waitcnt vmcnt(" #n ")" ::: "memory")
; #define PG8_WAIT_L(n) asm volatile("s_waitcnt lgkmcnt(" #n ")" ::: "memory")
; #define PG8_BAR __builtin_amdgcn_s_barrier()
; template <class Epi, class Sched, bool ALIGN_EPI = false, bool SP2 = false>
; __device__ __forceinline__ void gemm_phase(PG8_LAS unsigned char* lds, const Gemm g, const Sched& S, const Epi& E) {
;     ...
;             const char* a1 = cA + (size_t)(t + 1) * kstep;
;             const char* a2 = last ? nA : cA + (size_t)(t + 2) * kstep; const char* b2 = last ? nB : cB + (size_t)(t + 2) * kstep;
;             const char* a3 = a2 + kstep; const char* b3 = b2 + kstep;
;             if (last && has_next) S.a_ready(nxt);
;             if constexpr (SP2) {
;             PG8_LDB(B0, 0, 0); PG8_LDB(B1, 0, 1); PG8_SCHED; PG8_LDA(At, 0, 0); PG8_STAGE(PG8_SA(1, 1), a1 + hstep, voffA);
;             PG8_WAIT_V(8); PG8_WAIT_L(0); PG8_BAR; PG8_MMA(0, 0, At, B0); PG8_MMA(0, 1, At, B1); PG8_BAR; PG8_SCHED;
;             PG8_LDA(At, 0, 1); PG8_STAGE(PG8_SB(0, 0), b2, voffB); PG8_STAGE(PG8_SB(0, 1), b2 + hstep, voffB); PG8_STAGE(PG8_SA(0, 0), a2, voffA);
;             PG8_WAIT_V(8); PG8_WAIT_L(0); PG8_BAR; PG8_MMA(1, 0, At, B0); PG8_MMA(1, 1, At, B1); PG8_BAR; PG8_SCHED;
.LBB0_2096:
	s_add_u32 s27, s40, 0xfffc0080
	s_addc_u32 s29, s41, -1
	s_add_i32 s31, 0, 0x10000
	s_cmp_eq_u32 s26, 12
	s_cselect_b32 s45, s1, s29
	s_cselect_b32 s44, s0, s27
	s_cselect_b32 s43, s35, s13
	s_cselect_b32 s42, s34, s11
	s_add_i32 s27, 0, 0x14000
	ds_read_b128 v[178:181], v175 offset:16384
	ds_read_b128 v[204:207], v175 offset:17408
	ds_read_b128 v[208:211], v175 offset:18432
	ds_read_b128 v[212:215], v175 offset:19456
	s_add_i32 m0, s55, 0xc000
	ds_read_b128 v[216:219], v177
	ds_read_b128 v[220:223], v177 offset:1024
	ds_read_b128 v[224:227], v177 offset:2048
	ds_read_b128 v[228:231], v177 offset:3072
	ds_read_b128 v[232:235], v177 offset:4096
	ds_read_b128 v[236:239], v177 offset:5120
	ds_read_b128 v[240:243], v177 offset:6144
	ds_read_b128 v[244:247], v177 offset:7168
	global_load_lds_dwordx4 v150, s[40:41]
	s_add_i32 m0, s55, 0xe000
	s_nop 0
	global_load_lds_dwordx4 v152, s[40:41]
	s_waitcnt vmcnt(8) lgkmcnt(0)
	s_setprio 0
	s_barrier
	v_mfma_f32_16x16x32_bf16 v[130:133], v[134:137], v[216:219], v[130:133]
	v_mfma_f32_16x16x32_bf16 v[126:129], v[154:157], v[216:219], v[126:129]
	v_mfma_f32_16x16x32_bf16 v[122:125], v[134:137], v[224:227], v[122:125]
	v_mfma_f32_16x16x32_bf16 v[118:121], v[154:157], v[224:227], v[118:121]
	v_mfma_f32_16x16x32_bf16 v[114:117], v[134:137], v[232:235], v[114:117]
	v_mfma_f32_16x16x32_bf16 v[110:113], v[154:157], v[232:235], v[110:113]
	v_mfma_f32_16x16x32_bf16 v[106:109], v[134:137], v[240:243], v[106:109]
	v_mfma_f32_16x16x32_bf16 v[102:105], v[154:157], v[240:243], v[102:105]
	v_mfma_f32_16x16x32_bf16 v[130:133], v[138:141], v[220:223], v[130:133]
	v_mfma_f32_16x16x32_bf16 v[126:129], v[158:161], v[220:223], v[126:129]
	v_mfma_f32_16x16x32_bf16 v[122:125], v[138:141], v[228:231], v[122:125]
	v_mfma_f32_16x16x32_bf16 v[118:121], v[158:161], v[228:231], v[118:121]
	v_mfma_f32_16x16x32_bf16 v[114:117], v[138:141], v[236:239], v[114:117]
	v_mfma_f32_16x16x32_bf16 v[110:113], v[158:161], v[236:239], v[110:113]
	v_mfma_f32_16x16x32_bf16 v[106:109], v[138:141], v[244:247], v[106:109]
	v_mfma_f32_16x16x32_bf16 v[102:105], v[158:161], v[244:247], v[102:105]
	v_mfma_f32_16x16x32_bf16 v[98:101], v[178:181], v[216:219], v[98:101]
	v_mfma_f32_16x16x32_bf16 v[94:97], v[208:211], v[216:219], v[94:97]
	v_mfma_f32_16x16x32_bf16 v[90:93], v[178:181], v[224:227], v[90:93]
	v_mfma_f32_16x16x32_bf16 v[86:89], v[208:211], v[224:227], v[86:89]
	v_mfma_f32_16x16x32_bf16 v[82:85], v[178:181], v[232:235], v[82:85]
	v_mfma_f32_16x16x32_bf16 v[78:81], v[208:211], v[232:235], v[78:81]
	v_mfma_f32_16x16x32_bf16 v[74:77], v[178:181], v[240:243], v[74:77]
	v_mfma_f32_16x16x32_bf16 v[70:73], v[208:211], v[240:243], v[70:73]
	v_mfma_f32_16x16x32_bf16 v[98:101], v[204:207], v[220:223], v[98:101]
	v_mfma_f32_16x16x32_bf16 v[94:97], v[212:215], v[220:223], v[94:97]
	v_mfma_f32_16x16x32_bf16 v[90:93], v[204:207], v[228:231], v[90:93]
	v_mfma_f32_16x16x32_bf16 v[86:89], v[212:215], v[228:231], v[86:89]
	v_mfma_f32_16x16x32_bf16 v[82:85], v[204:207], v[236:239], v[82:85]
	v_mfma_f32_16x16x32_bf16 v[78:81], v[212:215], v[236:239], v[78:81]
	v_mfma_f32_16x16x32_bf16 v[74:77], v[204:207], v[244:247], v[74:77]
	v_mfma_f32_16x16x32_bf16 v[70:73], v[212:215], v[244:247], v[70:73]
	s_setprio 3
	s_barrier
	s_add_i32 s29, s31, s54
	s_mov_b32 m0, s29
	ds_read_b128 v[216:219], v177 offset:16384
	ds_read_b128 v[220:223], v177 offset:17408
	ds_read_b128 v[224:227], v177 offset:18432
	ds_read_b128 v[228:231], v177 offset:19456
	ds_read_b128 v[232:235], v177 offset:20480
	ds_read_b128 v[236:239], v177 offset:21504
	ds_read_b128 v[240:243], v177 offset:22528
	ds_read_b128 v[244:247], v177 offset:23552
	global_load_lds_dwordx4 v144, s[42:43]
	s_add_i32 m0, s29, 0x2000
	s_add_u32 s64, s42, 0x40000
	s_addc_u32 s65, s43, 0
	s_add_i32 s27, s27, s54
	global_load_lds_dwordx4 v148, s[42:43]
	s_mov_b32 m0, s27
	s_nop 0
	global_load_lds_dwordx4 v144, s[64:65]
	s_add_i32 m0, s27, 0x2000
	s_nop 0
	global_load_lds_dwordx4 v148, s[64:65]
	s_mov_b32 m0, s55
	s_nop 0
	global_load_lds_dwordx4 v142, s[44:45]
	s_mov_b32 m0, s56
	s_nop 0
	global_load_lds_dwordx4 v146, s[44:45]
	s_waitcnt vmcnt(8) lgkmcnt(0)
	s_setprio 0
	s_barrier
	v_mfma_f32_16x16x32_bf16 v[66:69], v[134:137], v[216:219], v[66:69]
	v_mfma_f32_16x16x32_bf16 v[62:65], v[154:157], v[216:219], v[62:65]
	v_mfma_f32_16x16x32_bf16 v[58:61], v[134:137], v[224:227], v[58:61]
	v_mfma_f32_16x16x32_bf16 v[54:57], v[154:157], v[224:227], v[54:57]
	v_mfma_f32_16x16x32_bf16 v[50:53], v[134:137], v[232:235], v[50:53]
	v_mfma_f32_16x16x32_bf16 v[46:49], v[154:157], v[232:235], v[46:49]
	v_mfma_f32_16x16x32_bf16 v[42:45], v[134:137], v[240:243], v[42:45]
	v_mfma_f32_16x16x32_bf16 v[38:41], v[154:157], v[240:243], v[38:41]
	v_mfma_f32_16x16x32_bf16 v[66:69], v[138:141], v[220:223], v[66:69]
	v_mfma_f32_16x16x32_bf16 v[62:65], v[158:161], v[220:223], v[62:65]
	v_mfma_f32_16x16x32_bf16 v[58:61], v[138:141], v[228:231], v[58:61]
	v_mfma_f32_16x16x32_bf16 v[54:57], v[158:161], v[228:231], v[54:57]
	v_mfma_f32_16x16x32_bf16 v[50:53], v[138:141], v[236:239], v[50:53]
	v_mfma_f32_16x16x32_bf16 v[46:49], v[158:161], v[236:239], v[46:49]
	v_mfma_f32_16x16x32_bf16 v[42:45], v[138:141], v[244:247], v[42:45]
	v_mfma_f32_16x16x32_bf16 v[38:41], v[158:161], v[244:247], v[38:41]
	v_mfma_f32_16x16x32_bf16 v[34:37], v[178:181], v[216:219], v[34:37]
	ds_read_b128 v[134:137], v175 offset:32768
	v_mfma_f32_16x16x32_bf16 v[30:33], v[208:211], v[216:219], v[30:33]
	ds_read_b128 v[138:141], v175 offset:33792
	v_mfma_f32_16x16x32_bf16 v[26:29], v[178:181], v[224:227], v[26:29]
	ds_read_b128 v[154:157], v175 offset:34816
	v_mfma_f32_16x16x32_bf16 v[22:25], v[208:211], v[224:227], v[22:25]
	ds_read_b128 v[158:161], v175 offset:35840
	v_mfma_f32_16x16x32_bf16 v[18:21], v[178:181], v[232:235], v[18:21]
	v_mfma_f32_16x16x32_bf16 v[14:17], v[208:211], v[232:235], v[14:17]
	v_mfma_f32_16x16x32_bf16 v[10:13], v[178:181], v[240:243], v[10:13]
	v_mfma_f32_16x16x32_bf16 v[4:7], v[208:211], v[240:243], v[6:9]
	v_mfma_f32_16x16x32_bf16 v[34:37], v[204:207], v[220:223], v[34:37]
	v_mfma_f32_16x16x32_bf16 v[30:33], v[212:215], v[220:223], v[30:33]
	v_mfma_f32_16x16x32_bf16 v[26:29], v[204:207], v[228:231], v[26:29]
	v_mfma_f32_16x16x32_bf16 v[22:25], v[212:215], v[228:231], v[22:25]
	v_mfma_f32_16x16x32_bf16 v[18:21], v[204:207], v[236:239], v[18:21]
	v_mfma_f32_16x16x32_bf16 v[14:17], v[212:215], v[236:239], v[14:17]
	v_mfma_f32_16x16x32_bf16 v[10:13], v[204:207], v[244:247], v[10:13]
	v_mfma_f32_16x16x32_bf16 v[4:7], v[212:215], v[244:247], v[4:7]
	s_setprio 3
	s_barrier
; #define PG8_STAGE(bufoff, gbase, voff) do { _Pragma("unroll") for (int _i = 0; _i < 2; ++_i) \
;         __builtin_amdgcn_global_load_lds((const unsigned*)((const char*)(gbase) + (voff)[_i]), (PG8_LAS unsigned*)(lds + (bufoff) + ldsw + _i * 8192), 16, 0, 0); } while (0)
; #define PG8_LDA(dst, b, h) do { _Pragma("unroll") for (int m = 0; m < 4; ++m) _Pragma("unroll") for (int k = 0; k < 2; ++k) dst[m][k] = *(const PG8_LAS bf16x8*)(lds + PG8_SA(b, h) + aoff + m * 2048 + k * 1024); } while (0)
; #define PG8_LDB(dst, b, h) do { _Pragma("unroll") for (int n = 0; n < 2; ++n) _Pragma("unroll") for (int k = 0; k < 2; ++k) dst[n][k] = *(const PG8_LAS bf16x8*)(lds + PG8_SB(b, h) + boff + n * 2048 + k * 1024); } while (0)
; #define PG8_MMA(ai, bj, At, Bt) do { __builtin_amdgcn_s_setprio(1); _Pragma("unroll") for (int m = 0; m < 4; ++m) _Pragma("unroll") for (int n = 0; n < 2; ++n) _Pragma("unroll") for (int k = 0; k < 2; ++k) \
;         acc[ai][bj][m][n] = __builtin_amdgcn_mfma_f32_16x16x32_bf16(Bt[n][k], At[m][k], acc[ai][bj][m][n], 0, 0, 0); __builtin_amdgcn_s_setprio(0); } while (0)
; #define PG8_WAIT_V(n) asm volatile("s_waitcnt vmcnt(" #n ")" ::: "memory")
; #define PG8_WAIT_L(n) asm volatile("s_waitcnt lgkmcnt(" #n ")" ::: "memory")
; #define PG8_BAR __builtin_amdgcn_s_barrier()
; #define PG8_SCHED __builtin_amdgcn_sched_barrier(0)
; template <class Epi, class Sched, bool ALIGN_EPI = false, bool SP2 = false>
; __device__ __forceinline__ void gemm_phase(PG8_LAS unsigned char* lds, const Gemm g, const Sched& S, const Epi& E) {
;     ...
;             PG8_LDB(B0, 1, 0); PG8_LDB(B1, 1, 1); PG8_SCHED; PG8_LDA(At, 1, 0); PG8_STAGE(PG8_SA(0, 1), a2 + hstep, voffA);
;             PG8_WAIT_V(8); PG8_WAIT_L(0); PG8_BAR; PG8_MMA(0, 0, At, B0); PG8_MMA(0, 1, At, B1); PG8_BAR; PG8_SCHED;
;             PG8_LDA(At, 1, 1); PG8_STAGE(PG8_SB(1, 0), b3, voffB); PG8_STAGE(PG8_SB(1, 1), b3 + hstep, voffB); PG8_STAGE(PG8_SA(1, 0), a3, voffA);
;             PG8_WAIT_V(8); PG8_WAIT_L(0); PG8_BAR; PG8_MMA(1, 0, At, B0); PG8_MMA(1, 1, At, B1); PG8_BAR; PG8_SCHED;
	s_add_i32 s27, 0, 0x18000
	s_add_i32 s29, 0, 0x1c000
	ds_read_b128 v[178:181], v175 offset:49152
	ds_read_b128 v[204:207], v175 offset:50176
	ds_read_b128 v[208:211], v175 offset:51200
	ds_read_b128 v[212:215], v175 offset:52224
	s_add_u32 s100, s44, 0x80
	s_addc_u32 s101, s45, 0
	s_add_u32 s44, s44, 0x40000
	s_addc_u32 s45, s45, 0
	s_mov_b32 m0, s57
	ds_read_b128 v[216:219], v177 offset:32768
	ds_read_b128 v[220:223], v177 offset:33792
	ds_read_b128 v[224:227], v177 offset:34816
	ds_read_b128 v[228:231], v177 offset:35840
	ds_read_b128 v[232:235], v177 offset:36864
	ds_read_b128 v[236:239], v177 offset:37888
	ds_read_b128 v[240:243], v177 offset:38912
	ds_read_b128 v[244:247], v177 offset:39936
	global_load_lds_dwordx4 v142, s[44:45]
	s_mov_b32 m0, s58
	s_nop 0
	global_load_lds_dwordx4 v146, s[44:45]
	s_waitcnt vmcnt(8) lgkmcnt(0)
	s_setprio 0
	s_barrier
	v_mfma_f32_16x16x32_bf16 v[130:133], v[134:137], v[216:219], v[130:133]
	v_mfma_f32_16x16x32_bf16 v[126:129], v[154:157], v[216:219], v[126:129]
	v_mfma_f32_16x16x32_bf16 v[122:125], v[134:137], v[224:227], v[122:125]
	v_mfma_f32_16x16x32_bf16 v[118:121], v[154:157], v[224:227], v[118:121]
	v_mfma_f32_16x16x32_bf16 v[114:117], v[134:137], v[232:235], v[114:117]
	v_mfma_f32_16x16x32_bf16 v[110:113], v[154:157], v[232:235], v[110:113]
	v_mfma_f32_16x16x32_bf16 v[106:109], v[134:137], v[240:243], v[106:109]
	v_mfma_f32_16x16x32_bf16 v[102:105], v[154:157], v[240:243], v[102:105]
	v_mfma_f32_16x16x32_bf16 v[130:133], v[138:141], v[220:223], v[130:133]
	v_mfma_f32_16x16x32_bf16 v[126:129], v[158:161], v[220:223], v[126:129]
	v_mfma_f32_16x16x32_bf16 v[122:125], v[138:141], v[228:231], v[122:125]
	v_mfma_f32_16x16x32_bf16 v[118:121], v[158:161], v[228:231], v[118:121]
	v_mfma_f32_16x16x32_bf16 v[114:117], v[138:141], v[236:239], v[114:117]
	v_mfma_f32_16x16x32_bf16 v[110:113], v[158:161], v[236:239], v[110:113]
	v_mfma_f32_16x16x32_bf16 v[106:109], v[138:141], v[244:247], v[106:109]
	v_mfma_f32_16x16x32_bf16 v[102:105], v[158:161], v[244:247], v[102:105]
	v_mfma_f32_16x16x32_bf16 v[98:101], v[178:181], v[216:219], v[98:101]
	v_mfma_f32_16x16x32_bf16 v[94:97], v[208:211], v[216:219], v[94:97]
	v_mfma_f32_16x16x32_bf16 v[90:93], v[178:181], v[224:227], v[90:93]
	v_mfma_f32_16x16x32_bf16 v[86:89], v[208:211], v[224:227], v[86:89]
	v_mfma_f32_16x16x32_bf16 v[82:85], v[178:181], v[232:235], v[82:85]
	v_mfma_f32_16x16x32_bf16 v[78:81], v[208:211], v[232:235], v[78:81]
	v_mfma_f32_16x16x32_bf16 v[74:77], v[178:181], v[240:243], v[74:77]
	v_mfma_f32_16x16x32_bf16 v[70:73], v[208:211], v[240:243], v[70:73]
	v_mfma_f32_16x16x32_bf16 v[98:101], v[204:207], v[220:223], v[98:101]
	v_mfma_f32_16x16x32_bf16 v[94:97], v[212:215], v[220:223], v[94:97]
	v_mfma_f32_16x16x32_bf16 v[90:93], v[204:207], v[228:231], v[90:93]
	v_mfma_f32_16x16x32_bf16 v[86:89], v[212:215], v[228:231], v[86:89]
	v_mfma_f32_16x16x32_bf16 v[82:85], v[204:207], v[236:239], v[82:85]
	v_mfma_f32_16x16x32_bf16 v[78:81], v[212:215], v[236:239], v[78:81]
	v_mfma_f32_16x16x32_bf16 v[74:77], v[204:207], v[244:247], v[74:77]
	v_mfma_f32_16x16x32_bf16 v[70:73], v[212:215], v[244:247], v[70:73]
	s_setprio 3
	s_barrier
	s_add_i32 s27, s27, s54
	s_add_i32 m0, s27, 0xffffff80
	ds_read_b128 v[216:219], v177 offset:49152
	ds_read_b128 v[220:223], v177 offset:50176
	ds_read_b128 v[224:227], v177 offset:51200
	ds_read_b128 v[228:231], v177 offset:52224
	ds_read_b128 v[232:235], v177 offset:53248
	ds_read_b128 v[236:239], v177 offset:54272
	ds_read_b128 v[240:243], v177 offset:55296
	ds_read_b128 v[244:247], v177 offset:56320
	global_load_lds_dwordx4 v144, s[42:43] offset:128
	s_add_i32 m0, s27, 0x1f80
	s_add_i32 s27, s29, s54
	global_load_lds_dwordx4 v148, s[42:43] offset:128
	s_add_u32 s42, s42, 0x40080
	s_addc_u32 s43, s43, 0
	s_mov_b32 m0, s27
	s_nop 0
	global_load_lds_dwordx4 v144, s[42:43]
	s_add_i32 m0, s27, 0x2000
	s_nop 0
	global_load_lds_dwordx4 v148, s[42:43]
	s_mov_b32 m0, s61
	s_nop 0
	global_load_lds_dwordx4 v142, s[100:101]
	s_mov_b32 m0, s62
	s_nop 0
	global_load_lds_dwordx4 v146, s[100:101]
	s_nop 0
	s_waitcnt vmcnt(8) lgkmcnt(0)
	s_setprio 0
	s_barrier
	v_mfma_f32_16x16x32_bf16 v[66:69], v[134:137], v[216:219], v[66:69]
	v_mfma_f32_16x16x32_bf16 v[62:65], v[154:157], v[216:219], v[62:65]
	v_mfma_f32_16x16x32_bf16 v[58:61], v[134:137], v[224:227], v[58:61]
	v_mfma_f32_16x16x32_bf16 v[54:57], v[154:157], v[224:227], v[54:57]
	v_mfma_f32_16x16x32_bf16 v[50:53], v[134:137], v[232:235], v[50:53]
	v_mfma_f32_16x16x32_bf16 v[46:49], v[154:157], v[232:235], v[46:49]
	v_mfma_f32_16x16x32_bf16 v[42:45], v[134:137], v[240:243], v[42:45]
	v_mfma_f32_16x16x32_bf16 v[38:41], v[154:157], v[240:243], v[38:41]
	v_mfma_f32_16x16x32_bf16 v[66:69], v[138:141], v[220:223], v[66:69]
	v_mfma_f32_16x16x32_bf16 v[62:65], v[158:161], v[220:223], v[62:65]
	v_mfma_f32_16x16x32_bf16 v[58:61], v[138:141], v[228:231], v[58:61]
	v_mfma_f32_16x16x32_bf16 v[54:57], v[158:161], v[228:231], v[54:57]
	v_mfma_f32_16x16x32_bf16 v[50:53], v[138:141], v[236:239], v[50:53]
	v_mfma_f32_16x16x32_bf16 v[46:49], v[158:161], v[236:239], v[46:49]
	v_mfma_f32_16x16x32_bf16 v[42:45], v[138:141], v[244:247], v[42:45]
	v_mfma_f32_16x16x32_bf16 v[38:41], v[158:161], v[244:247], v[38:41]
	v_mfma_f32_16x16x32_bf16 v[34:37], v[178:181], v[216:219], v[34:37]
	ds_read_b128 v[134:137], v175
	v_mfma_f32_16x16x32_bf16 v[30:33], v[208:211], v[216:219], v[30:33]
	ds_read_b128 v[138:141], v175 offset:1024
	v_mfma_f32_16x16x32_bf16 v[26:29], v[178:181], v[224:227], v[26:29]
	ds_read_b128 v[154:157], v175 offset:2048
	v_mfma_f32_16x16x32_bf16 v[22:25], v[208:211], v[224:227], v[22:25]
	ds_read_b128 v[158:161], v175 offset:3072
	v_mfma_f32_16x16x32_bf16 v[18:21], v[178:181], v[232:235], v[18:21]
	v_mfma_f32_16x16x32_bf16 v[14:17], v[208:211], v[232:235], v[14:17]
	v_mfma_f32_16x16x32_bf16 v[8:11], v[178:181], v[240:243], v[10:13]
	v_mfma_f32_16x16x32_bf16 v[4:7], v[208:211], v[240:243], v[4:7]
	v_mfma_f32_16x16x32_bf16 v[34:37], v[204:207], v[220:223], v[34:37]
	v_mfma_f32_16x16x32_bf16 v[30:33], v[212:215], v[220:223], v[30:33]
	v_mfma_f32_16x16x32_bf16 v[26:29], v[204:207], v[228:231], v[26:29]
	v_mfma_f32_16x16x32_bf16 v[22:25], v[212:215], v[228:231], v[22:25]
	v_mfma_f32_16x16x32_bf16 v[18:21], v[204:207], v[236:239], v[18:21]
	v_mfma_f32_16x16x32_bf16 v[14:17], v[212:215], v[236:239], v[14:17]
	v_mfma_f32_16x16x32_bf16 v[10:13], v[204:207], v[244:247], v[8:11]
	v_mfma_f32_16x16x32_bf16 v[6:9], v[212:215], v[244:247], v[4:7]
	s_setprio 3
	s_barrier
	s_add_i32 s26, s26, 2
	s_add_u32 s40, s40, 0x100
	s_addc_u32 s41, s41, 0
	s_add_u32 s11, s11, 0x100
	s_addc_u32 s13, s13, 0
	s_cmp_gt_u32 s26, 13
	s_cbranch_scc0 .LBB0_2096
	s_and_b64 vcc, exec, s[8:9]
	s_cbranch_vccz .LBB0_2099
	s_barrier

; #define PG8_STAGE(bufoff, gbase, voff) do { _Pragma("unroll") for (int _i = 0; _i < 2; ++_i) \
;         __builtin_amdgcn_global_load_lds((const unsigned*)((const char*)(gbase) + (voff)[_i]), (PG8_LAS unsigned*)(lds + (bufoff) + ldsw + _i * 8192), 16, 0, 0); } while (0)
; #define PG8_LDA(dst, b, h) do { _Pragma("unroll") for (int m = 0; m < 4; ++m) _Pragma("unroll") for (int k = 0; k < 2; ++k) dst[m][k] = *(const PG8_LAS bf16x8*)(lds + PG8_SA(b, h) + aoff + m * 2048 + k * 1024); } while (0)
; #define PG8_LDB(dst, b, h) do { _Pragma("unroll") for (int n = 0; n < 2; ++n) _Pragma("unroll") for (int k = 0; k < 2; ++k) dst[n][k] = *(const PG8_LAS bf16x8*)(lds + PG8_SB(b, h) + boff + n * 2048 + k * 1024); } while (0)
; #define PG8_MMA(ai, bj, At, Bt) do { __builtin_amdgcn_s_setprio(1); _Pragma("unroll") for (int m = 0; m < 4; ++m) _Pragma("unroll") for (int n = 0; n < 2; ++n) _Pragma("unroll") for (int k = 0; k < 2; ++k) \
;         acc[ai][bj][m][n] = __builtin_amdgcn_mfma_f32_16x16x32_bf16(Bt[n][k], At[m][k], acc[ai][bj][m][n], 0, 0, 0); __builtin_amdgcn_s_setprio(0); } while (0)
; #define PG8_WAIT_V(n) asm volatile("s_waitcnt vmcnt(" #n ")" ::: "memory")
; #define PG8_WAIT_L(n) asm volatile("s_waitcnt lgkmcnt(" #n ")" ::: "memory")
; #define PG8_BAR __builtin_amdgcn_s_barrier()
; template <class Epi, class Sched, bool ALIGN_EPI = false, bool SP2 = false>
; __device__ __forceinline__ void gemm_phase(PG8_LAS unsigned char* lds, const Gemm g, const Sched& S, const Epi& E) {
;     ...
;             const char* a1 = cA + (size_t)(t + 1) * kstep;
;             const char* a2 = last ? nA : cA + (size_t)(t + 2) * kstep; const char* b2 = last ? nB : cB + (size_t)(t + 2) * kstep;
;             const char* a3 = a2 + kstep; const char* b3 = b2 + kstep;
;             if (last && has_next) S.a_ready(nxt);
;             if constexpr (SP2) {
;             PG8_LDB(B0, 0, 0); PG8_LDB(B1, 0, 1); PG8_SCHED; PG8_LDA(At, 0, 0); PG8_STAGE(PG8_SA(1, 1), a1 + hstep, voffA);
;             PG8_WAIT_V(8); PG8_WAIT_L(0); PG8_BAR; PG8_MMA(0, 0, At, B0); PG8_MMA(0, 1, At, B1); PG8_BAR; PG8_SCHED;
;             PG8_LDA(At, 0, 1); PG8_STAGE(PG8_SB(0, 0), b2, voffB); PG8_STAGE(PG8_SB(0, 1), b2 + hstep, voffB); PG8_STAGE(PG8_SA(0, 0), a2, voffA);
;             PG8_WAIT_V(8); PG8_WAIT_L(0); PG8_BAR; PG8_MMA(1, 0, At, B0); PG8_MMA(1, 1, At, B1); PG8_BAR; PG8_SCHED;
.LBB0_2185:
	s_add_u32 s42, s40, 0x100
	s_addc_u32 s43, s41, 0
	s_add_i32 s37, 0, 0x10000
	s_cmp_eq_u32 s31, 28
	s_cselect_b32 s47, s5, s43
	s_cselect_b32 s46, s4, s42
	s_cselect_b32 s45, s35, s29
	s_cselect_b32 s44, s34, s2
	s_add_i32 s39, 0, 0x14000
	ds_read_b128 v[158:161], v243 offset:16384
	ds_read_b128 v[174:177], v243 offset:17408
	ds_read_b128 v[180:183], v243 offset:18432
	ds_read_b128 v[204:207], v243 offset:19456
	v_lshl_add_u64 v[162:163], s[40:41], 0, v[138:139]
	s_add_i32 m0, s55, 0xc000
	ds_read_b128 v[208:211], v179
	ds_read_b128 v[212:215], v179 offset:1024
	ds_read_b128 v[216:219], v179 offset:2048
	ds_read_b128 v[220:223], v179 offset:3072
	ds_read_b128 v[224:227], v179 offset:4096
	ds_read_b128 v[228:231], v179 offset:5120
	ds_read_b128 v[232:235], v179 offset:6144
	ds_read_b128 v[236:239], v179 offset:7168
	global_load_lds_dwordx4 v[162:163], off
	v_lshl_add_u64 v[162:163], s[40:41], 0, v[140:141]
	s_add_i32 m0, s55, 0xe000
	s_nop 0
	global_load_lds_dwordx4 v[162:163], off
	s_waitcnt vmcnt(8) lgkmcnt(0)
	s_setprio 0
	s_barrier
	v_mfma_f32_16x16x32_bf16 v[128:131], v[142:145], v[208:211], v[128:131]
	v_mfma_f32_16x16x32_bf16 v[124:127], v[150:153], v[208:211], v[124:127]
	v_mfma_f32_16x16x32_bf16 v[112:115], v[142:145], v[216:219], v[112:115]
	v_mfma_f32_16x16x32_bf16 v[108:111], v[150:153], v[216:219], v[108:111]
	v_mfma_f32_16x16x32_bf16 v[96:99], v[142:145], v[224:227], v[96:99]
	v_mfma_f32_16x16x32_bf16 v[92:95], v[150:153], v[224:227], v[92:95]
	v_mfma_f32_16x16x32_bf16 v[80:83], v[142:145], v[232:235], v[80:83]
	v_mfma_f32_16x16x32_bf16 v[76:79], v[150:153], v[232:235], v[76:79]
	v_mfma_f32_16x16x32_bf16 v[128:131], v[146:149], v[212:215], v[128:131]
	v_mfma_f32_16x16x32_bf16 v[124:127], v[154:157], v[212:215], v[124:127]
	v_mfma_f32_16x16x32_bf16 v[112:115], v[146:149], v[220:223], v[112:115]
	v_mfma_f32_16x16x32_bf16 v[108:111], v[154:157], v[220:223], v[108:111]
	v_mfma_f32_16x16x32_bf16 v[96:99], v[146:149], v[228:231], v[96:99]
	v_mfma_f32_16x16x32_bf16 v[92:95], v[154:157], v[228:231], v[92:95]
	v_mfma_f32_16x16x32_bf16 v[80:83], v[146:149], v[236:239], v[80:83]
	v_mfma_f32_16x16x32_bf16 v[76:79], v[154:157], v[236:239], v[76:79]
	v_mfma_f32_16x16x32_bf16 v[120:123], v[158:161], v[208:211], v[120:123]
	v_mfma_f32_16x16x32_bf16 v[116:119], v[180:183], v[208:211], v[116:119]
	v_mfma_f32_16x16x32_bf16 v[104:107], v[158:161], v[216:219], v[104:107]
	v_mfma_f32_16x16x32_bf16 v[100:103], v[180:183], v[216:219], v[100:103]
	v_mfma_f32_16x16x32_bf16 v[88:91], v[158:161], v[224:227], v[88:91]
	v_mfma_f32_16x16x32_bf16 v[84:87], v[180:183], v[224:227], v[84:87]
	v_mfma_f32_16x16x32_bf16 v[72:75], v[158:161], v[232:235], v[72:75]
	v_mfma_f32_16x16x32_bf16 v[68:71], v[180:183], v[232:235], v[68:71]
	v_mfma_f32_16x16x32_bf16 v[120:123], v[174:177], v[212:215], v[120:123]
	v_mfma_f32_16x16x32_bf16 v[116:119], v[204:207], v[212:215], v[116:119]
	v_mfma_f32_16x16x32_bf16 v[104:107], v[174:177], v[220:223], v[104:107]
	v_mfma_f32_16x16x32_bf16 v[100:103], v[204:207], v[220:223], v[100:103]
	v_mfma_f32_16x16x32_bf16 v[88:91], v[174:177], v[228:231], v[88:91]
	v_mfma_f32_16x16x32_bf16 v[84:87], v[204:207], v[228:231], v[84:87]
	v_mfma_f32_16x16x32_bf16 v[72:75], v[174:177], v[236:239], v[72:75]
	v_mfma_f32_16x16x32_bf16 v[68:71], v[204:207], v[236:239], v[68:71]
	s_setprio 3
	s_barrier
	s_add_i32 s37, s37, s54
	s_mov_b32 m0, s37
	ds_read_b128 v[208:211], v179 offset:16384
	ds_read_b128 v[212:215], v179 offset:17408
	ds_read_b128 v[216:219], v179 offset:18432
	ds_read_b128 v[220:223], v179 offset:19456
	ds_read_b128 v[224:227], v179 offset:20480
	ds_read_b128 v[228:231], v179 offset:21504
	ds_read_b128 v[232:235], v179 offset:22528
	ds_read_b128 v[236:239], v179 offset:23552
	global_load_lds_dwordx4 v2, s[44:45]
	s_add_i32 m0, s37, 0x2000
	s_add_u32 s40, s44, 0x80000
	s_addc_u32 s41, s45, 0
	s_add_i32 s37, s39, s54
	global_load_lds_dwordx4 v132, s[44:45]
	s_mov_b32 m0, s37
	s_nop 0
	global_load_lds_dwordx4 v2, s[40:41]
	s_add_i32 m0, s37, 0x2000
	s_nop 0
	global_load_lds_dwordx4 v132, s[40:41]
	s_mov_b32 m0, s55
	s_nop 0
	global_load_lds_dwordx4 v2, s[46:47]
	s_mov_b32 m0, s56
	s_nop 0
	global_load_lds_dwordx4 v132, s[46:47]
	s_waitcnt vmcnt(8) lgkmcnt(0)
	s_setprio 0
	s_barrier
	v_mfma_f32_16x16x32_bf16 v[64:67], v[142:145], v[208:211], v[64:67]
	v_mfma_f32_16x16x32_bf16 v[60:63], v[150:153], v[208:211], v[60:63]
	v_mfma_f32_16x16x32_bf16 v[48:51], v[142:145], v[216:219], v[48:51]
	v_mfma_f32_16x16x32_bf16 v[44:47], v[150:153], v[216:219], v[44:47]
	v_mfma_f32_16x16x32_bf16 v[32:35], v[142:145], v[224:227], v[32:35]
	v_mfma_f32_16x16x32_bf16 v[28:31], v[150:153], v[224:227], v[28:31]
	v_mfma_f32_16x16x32_bf16 v[16:19], v[142:145], v[232:235], v[16:19]
	v_mfma_f32_16x16x32_bf16 v[12:15], v[150:153], v[232:235], v[12:15]
	v_mfma_f32_16x16x32_bf16 v[64:67], v[146:149], v[212:215], v[64:67]
	v_mfma_f32_16x16x32_bf16 v[60:63], v[154:157], v[212:215], v[60:63]
	v_mfma_f32_16x16x32_bf16 v[48:51], v[146:149], v[220:223], v[48:51]
	v_mfma_f32_16x16x32_bf16 v[44:47], v[154:157], v[220:223], v[44:47]
	v_mfma_f32_16x16x32_bf16 v[32:35], v[146:149], v[228:231], v[32:35]
	v_mfma_f32_16x16x32_bf16 v[28:31], v[154:157], v[228:231], v[28:31]
	v_mfma_f32_16x16x32_bf16 v[16:19], v[146:149], v[236:239], v[16:19]
	v_mfma_f32_16x16x32_bf16 v[12:15], v[154:157], v[236:239], v[12:15]
	v_mfma_f32_16x16x32_bf16 v[56:59], v[158:161], v[208:211], v[56:59]
	ds_read_b128 v[142:145], v243 offset:32768
	v_mfma_f32_16x16x32_bf16 v[52:55], v[180:183], v[208:211], v[52:55]
	ds_read_b128 v[146:149], v243 offset:33792
	v_mfma_f32_16x16x32_bf16 v[40:43], v[158:161], v[216:219], v[40:43]
	ds_read_b128 v[150:153], v243 offset:34816
	v_mfma_f32_16x16x32_bf16 v[36:39], v[180:183], v[216:219], v[36:39]
	ds_read_b128 v[154:157], v243 offset:35840
	v_mfma_f32_16x16x32_bf16 v[24:27], v[158:161], v[224:227], v[24:27]
	v_mfma_f32_16x16x32_bf16 v[20:23], v[180:183], v[224:227], v[20:23]
	v_mfma_f32_16x16x32_bf16 v[8:11], v[158:161], v[232:235], v[8:11]
	v_mfma_f32_16x16x32_bf16 v[4:7], v[180:183], v[232:235], v[4:7]
	v_mfma_f32_16x16x32_bf16 v[56:59], v[174:177], v[212:215], v[56:59]
	v_mfma_f32_16x16x32_bf16 v[52:55], v[204:207], v[212:215], v[52:55]
	v_mfma_f32_16x16x32_bf16 v[40:43], v[174:177], v[220:223], v[40:43]
	v_mfma_f32_16x16x32_bf16 v[36:39], v[204:207], v[220:223], v[36:39]
	v_mfma_f32_16x16x32_bf16 v[24:27], v[174:177], v[228:231], v[24:27]
	v_mfma_f32_16x16x32_bf16 v[20:23], v[204:207], v[228:231], v[20:23]
	v_mfma_f32_16x16x32_bf16 v[8:11], v[174:177], v[236:239], v[8:11]
	v_mfma_f32_16x16x32_bf16 v[4:7], v[204:207], v[236:239], v[4:7]
	s_setprio 3
	s_barrier
; #define PG8_STAGE(bufoff, gbase, voff) do { _Pragma("unroll") for (int _i = 0; _i < 2; ++_i) \
;         __builtin_amdgcn_global_load_lds((const unsigned*)((const char*)(gbase) + (voff)[_i]), (PG8_LAS unsigned*)(lds + (bufoff) + ldsw + _i * 8192), 16, 0, 0); } while (0)
; #define PG8_LDA(dst, b, h) do { _Pragma("unroll") for (int m = 0; m < 4; ++m) _Pragma("unroll") for (int k = 0; k < 2; ++k) dst[m][k] = *(const PG8_LAS bf16x8*)(lds + PG8_SA(b, h) + aoff + m * 2048 + k * 1024); } while (0)
; #define PG8_LDB(dst, b, h) do { _Pragma("unroll") for (int n = 0; n < 2; ++n) _Pragma("unroll") for (int k = 0; k < 2; ++k) dst[n][k] = *(const PG8_LAS bf16x8*)(lds + PG8_SB(b, h) + boff + n * 2048 + k * 1024); } while (0)
; #define PG8_MMA(ai, bj, At, Bt) do { __builtin_amdgcn_s_setprio(1); _Pragma("unroll") for (int m = 0; m < 4; ++m) _Pragma("unroll") for (int n = 0; n < 2; ++n) _Pragma("unroll") for (int k = 0; k < 2; ++k) \
;         acc[ai][bj][m][n] = __builtin_amdgcn_mfma_f32_16x16x32_bf16(Bt[n][k], At[m][k], acc[ai][bj][m][n], 0, 0, 0); __builtin_amdgcn_s_setprio(0); } while (0)
; #define PG8_WAIT_V(n) asm volatile("s_waitcnt vmcnt(" #n ")" ::: "memory")
; #define PG8_WAIT_L(n) asm volatile("s_waitcnt lgkmcnt(" #n ")" ::: "memory")
; #define PG8_BAR __builtin_amdgcn_s_barrier()
; #define PG8_SCHED __builtin_amdgcn_sched_barrier(0)
; template <class Epi, class Sched, bool ALIGN_EPI = false, bool SP2 = false>
; __device__ __forceinline__ void gemm_phase(PG8_LAS unsigned char* lds, const Gemm g, const Sched& S, const Epi& E) {
;     ...
;             PG8_LDB(B0, 1, 0); PG8_LDB(B1, 1, 1); PG8_SCHED; PG8_LDA(At, 1, 0); PG8_STAGE(PG8_SA(0, 1), a2 + hstep, voffA);
;             PG8_WAIT_V(8); PG8_WAIT_L(0); PG8_BAR; PG8_MMA(0, 0, At, B0); PG8_MMA(0, 1, At, B1); PG8_BAR; PG8_SCHED;
;             PG8_LDA(At, 1, 1); PG8_STAGE(PG8_SB(1, 0), b3, voffB); PG8_STAGE(PG8_SB(1, 1), b3 + hstep, voffB); PG8_STAGE(PG8_SA(1, 0), a3, voffA);
;             PG8_WAIT_V(8); PG8_WAIT_L(0); PG8_BAR; PG8_MMA(1, 0, At, B0); PG8_MMA(1, 1, At, B1); PG8_BAR; PG8_SCHED;
	s_add_i32 s37, 0, 0x18000
	s_add_i32 s39, 0, 0x1c000
	ds_read_b128 v[158:161], v243 offset:49152
	ds_read_b128 v[174:177], v243 offset:50176
	ds_read_b128 v[180:183], v243 offset:51200
	ds_read_b128 v[204:207], v243 offset:52224
	s_add_u32 s40, s46, 0x80000
	s_addc_u32 s41, s47, 0
	s_mov_b32 m0, s57
	ds_read_b128 v[208:211], v179 offset:32768
	ds_read_b128 v[212:215], v179 offset:33792
	ds_read_b128 v[216:219], v179 offset:34816
	ds_read_b128 v[220:223], v179 offset:35840
	ds_read_b128 v[224:227], v179 offset:36864
	ds_read_b128 v[228:231], v179 offset:37888
	ds_read_b128 v[232:235], v179 offset:38912
	ds_read_b128 v[236:239], v179 offset:39936
	global_load_lds_dwordx4 v2, s[40:41]
	s_mov_b32 m0, s58
	s_nop 0
	global_load_lds_dwordx4 v132, s[40:41]
	s_nop 0
	s_waitcnt vmcnt(8) lgkmcnt(0)
	s_setprio 0
	s_barrier
	v_mfma_f32_16x16x32_bf16 v[128:131], v[142:145], v[208:211], v[128:131]
	v_mfma_f32_16x16x32_bf16 v[124:127], v[150:153], v[208:211], v[124:127]
	v_mfma_f32_16x16x32_bf16 v[112:115], v[142:145], v[216:219], v[112:115]
	v_mfma_f32_16x16x32_bf16 v[108:111], v[150:153], v[216:219], v[108:111]
	v_mfma_f32_16x16x32_bf16 v[96:99], v[142:145], v[224:227], v[96:99]
	v_mfma_f32_16x16x32_bf16 v[92:95], v[150:153], v[224:227], v[92:95]
	v_mfma_f32_16x16x32_bf16 v[80:83], v[142:145], v[232:235], v[80:83]
	v_mfma_f32_16x16x32_bf16 v[76:79], v[150:153], v[232:235], v[76:79]
	v_mfma_f32_16x16x32_bf16 v[128:131], v[146:149], v[212:215], v[128:131]
	v_mfma_f32_16x16x32_bf16 v[124:127], v[154:157], v[212:215], v[124:127]
	v_mfma_f32_16x16x32_bf16 v[112:115], v[146:149], v[220:223], v[112:115]
	v_mfma_f32_16x16x32_bf16 v[108:111], v[154:157], v[220:223], v[108:111]
	v_mfma_f32_16x16x32_bf16 v[96:99], v[146:149], v[228:231], v[96:99]
	v_mfma_f32_16x16x32_bf16 v[92:95], v[154:157], v[228:231], v[92:95]
	v_mfma_f32_16x16x32_bf16 v[80:83], v[146:149], v[236:239], v[80:83]
	v_mfma_f32_16x16x32_bf16 v[76:79], v[154:157], v[236:239], v[76:79]
	v_mfma_f32_16x16x32_bf16 v[120:123], v[158:161], v[208:211], v[120:123]
	v_mfma_f32_16x16x32_bf16 v[116:119], v[180:183], v[208:211], v[116:119]
	v_mfma_f32_16x16x32_bf16 v[104:107], v[158:161], v[216:219], v[104:107]
	v_mfma_f32_16x16x32_bf16 v[100:103], v[180:183], v[216:219], v[100:103]
	v_mfma_f32_16x16x32_bf16 v[88:91], v[158:161], v[224:227], v[88:91]
	v_mfma_f32_16x16x32_bf16 v[84:87], v[180:183], v[224:227], v[84:87]
	v_mfma_f32_16x16x32_bf16 v[72:75], v[158:161], v[232:235], v[72:75]
	v_mfma_f32_16x16x32_bf16 v[68:71], v[180:183], v[232:235], v[68:71]
	v_mfma_f32_16x16x32_bf16 v[120:123], v[174:177], v[212:215], v[120:123]
	v_mfma_f32_16x16x32_bf16 v[116:119], v[204:207], v[212:215], v[116:119]
	v_mfma_f32_16x16x32_bf16 v[104:107], v[174:177], v[220:223], v[104:107]
	v_mfma_f32_16x16x32_bf16 v[100:103], v[204:207], v[220:223], v[100:103]
	v_mfma_f32_16x16x32_bf16 v[88:91], v[174:177], v[228:231], v[88:91]
	v_mfma_f32_16x16x32_bf16 v[84:87], v[204:207], v[228:231], v[84:87]
	v_mfma_f32_16x16x32_bf16 v[72:75], v[174:177], v[236:239], v[72:75]
	v_mfma_f32_16x16x32_bf16 v[68:71], v[204:207], v[236:239], v[68:71]
	s_setprio 3
	s_barrier
	s_add_i32 s37, s37, s54
	s_add_i32 m0, s37, 0xffffff80
	ds_read_b128 v[208:211], v179 offset:49152
	ds_read_b128 v[212:215], v179 offset:50176
	ds_read_b128 v[216:219], v179 offset:51200
	ds_read_b128 v[220:223], v179 offset:52224
	ds_read_b128 v[224:227], v179 offset:53248
	ds_read_b128 v[228:231], v179 offset:54272
	ds_read_b128 v[232:235], v179 offset:55296
	ds_read_b128 v[236:239], v179 offset:56320
	global_load_lds_dwordx4 v2, s[44:45] offset:128
	s_add_i32 m0, s37, 0x1f80
	s_add_u32 s40, s44, 0x80080
	s_addc_u32 s41, s45, 0
	s_add_i32 s37, s39, s54
	global_load_lds_dwordx4 v132, s[44:45] offset:128
	s_mov_b32 m0, s37
	s_nop 0
	global_load_lds_dwordx4 v2, s[40:41]
	s_add_i32 m0, s37, 0x2000
	s_nop 0
	global_load_lds_dwordx4 v132, s[40:41]
	s_add_i32 m0, s60, 0xffffff80
	s_nop 0
	global_load_lds_dwordx4 v2, s[46:47] offset:128
	s_add_i32 m0, s61, 0xffffff80
	s_nop 0
	global_load_lds_dwordx4 v132, s[46:47] offset:128
	s_nop 0
	s_waitcnt vmcnt(8) lgkmcnt(0)
	s_setprio 0
	s_barrier
	v_mfma_f32_16x16x32_bf16 v[64:67], v[142:145], v[208:211], v[64:67]
	v_mfma_f32_16x16x32_bf16 v[60:63], v[150:153], v[208:211], v[60:63]
	v_mfma_f32_16x16x32_bf16 v[48:51], v[142:145], v[216:219], v[48:51]
	v_mfma_f32_16x16x32_bf16 v[44:47], v[150:153], v[216:219], v[44:47]
	v_mfma_f32_16x16x32_bf16 v[32:35], v[142:145], v[224:227], v[32:35]
	v_mfma_f32_16x16x32_bf16 v[28:31], v[150:153], v[224:227], v[28:31]
	v_mfma_f32_16x16x32_bf16 v[16:19], v[142:145], v[232:235], v[16:19]
	v_mfma_f32_16x16x32_bf16 v[12:15], v[150:153], v[232:235], v[12:15]
	v_mfma_f32_16x16x32_bf16 v[64:67], v[146:149], v[212:215], v[64:67]
	v_mfma_f32_16x16x32_bf16 v[60:63], v[154:157], v[212:215], v[60:63]
	v_mfma_f32_16x16x32_bf16 v[48:51], v[146:149], v[220:223], v[48:51]
	v_mfma_f32_16x16x32_bf16 v[44:47], v[154:157], v[220:223], v[44:47]
	v_mfma_f32_16x16x32_bf16 v[32:35], v[146:149], v[228:231], v[32:35]
	v_mfma_f32_16x16x32_bf16 v[28:31], v[154:157], v[228:231], v[28:31]
	v_mfma_f32_16x16x32_bf16 v[16:19], v[146:149], v[236:239], v[16:19]
	v_mfma_f32_16x16x32_bf16 v[12:15], v[154:157], v[236:239], v[12:15]
	v_mfma_f32_16x16x32_bf16 v[56:59], v[158:161], v[208:211], v[56:59]
	ds_read_b128 v[142:145], v243
	v_mfma_f32_16x16x32_bf16 v[52:55], v[180:183], v[208:211], v[52:55]
	ds_read_b128 v[146:149], v243 offset:1024
	v_mfma_f32_16x16x32_bf16 v[40:43], v[158:161], v[216:219], v[40:43]
	ds_read_b128 v[150:153], v243 offset:2048
	v_mfma_f32_16x16x32_bf16 v[36:39], v[180:183], v[216:219], v[36:39]
	ds_read_b128 v[154:157], v243 offset:3072
	v_mfma_f32_16x16x32_bf16 v[24:27], v[158:161], v[224:227], v[24:27]
	v_mfma_f32_16x16x32_bf16 v[20:23], v[180:183], v[224:227], v[20:23]
	v_mfma_f32_16x16x32_bf16 v[8:11], v[158:161], v[232:235], v[8:11]
	v_mfma_f32_16x16x32_bf16 v[4:7], v[180:183], v[232:235], v[4:7]
	v_mfma_f32_16x16x32_bf16 v[56:59], v[174:177], v[212:215], v[56:59]
	v_mfma_f32_16x16x32_bf16 v[52:55], v[204:207], v[212:215], v[52:55]
	v_mfma_f32_16x16x32_bf16 v[40:43], v[174:177], v[220:223], v[40:43]
	v_mfma_f32_16x16x32_bf16 v[36:39], v[204:207], v[220:223], v[36:39]
	v_mfma_f32_16x16x32_bf16 v[24:27], v[174:177], v[228:231], v[24:27]
	v_mfma_f32_16x16x32_bf16 v[20:23], v[204:207], v[228:231], v[20:23]
	v_mfma_f32_16x16x32_bf16 v[8:11], v[174:177], v[236:239], v[8:11]
	v_mfma_f32_16x16x32_bf16 v[4:7], v[204:207], v[236:239], v[4:7]
	s_setprio 3
	s_barrier
	s_add_i32 s31, s31, 2
	s_add_u32 s2, s2, 0x100
	s_addc_u32 s29, s29, 0
	s_cmp_gt_u32 s31, 29
	s_mov_b64 s[40:41], s[42:43]
	s_cbranch_scc0 .LBB0_2185
	s_and_b64 vcc, exec, s[26:27]
	s_cbranch_vccz .LBB0_2188
	s_barrier
